# gemm_out with 256x256 tiles: the gemm_in tile code re-used (cloned, relabeled) with the w_out weights, 4 column tiles per panel and the plain bf16 d-store epilogue; old 256x128 loop bypassed
# speedup vs baseline: 1.0265x; 1.0108x over previous
.LBB0_1181:
	s_or_b64 exec, exec, s[76:77]
	v_mov_b32_e32 v0, v143
	s_and_b64 vcc, exec, s[72:73]
	s_mov_b32 s94, 0x20000
	s_mov_b32 s95, 0x60000
	s_add_u32 s86, s50, 0x108dd000
	s_addc_u32 s87, s51, 0
	s_movk_i32 s88, 0x800
	s_cbranch_vccz .Lgo_234
	v_readlane_b32 s6, v255, 23
	s_mov_b32 s1, 0
	s_mov_b32 s0, 0
	v_readlane_b32 s4, v253, 0
	v_readlane_b32 s7, v255, 24
	s_mov_b32 s5, s6
	s_branch .Lgo_235

.Lgo_235:
	s_and_b32 s1, 0xffff, s1
	s_and_b64 s[6:7], s[90:91], exec
	s_movk_i32 s6, 0x80
	s_cselect_b32 s6, s6, 0x88
	s_lshr_b32 s1, s6, s1
	s_lshl_b32 s6, s1, 2
	s_cmp_ge_i32 s4, s6
	s_cbranch_scc1 .Lgo_end
	v_ashrrev_i32_e32 v1, 6, v0
	v_lshrrev_b32_e32 v3, 30, v1
	v_add_u32_e32 v3, v1, v3
	s_mul_i32 s7, s0, s1
	s_lshl_b32 s0, s74, 21
	s_add_u32 s0, s0, 0xc40000
	v_ashrrev_i32_e32 v3, 2, v3
	s_add_u32 s0, s50, s0
	s_waitcnt vmcnt(6)
	v_and_b32_e32 v4, 7, v0
	v_mul_i32_i24_e32 v8, 4, v3
	s_addc_u32 s1, s51, 0
	v_and_b32_e32 v2, 31, v0
	v_lshlrev_b32_e32 v128, 4, v4
	v_sub_u32_e32 v9, v1, v8
	v_lshlrev_b32_e32 v153, 7, v3
	v_ashrrev_i32_e32 v152, 3, v0
	v_bfe_u32 v6, v0, 5, 1
	v_readlane_b32 s8, v253, 38
	v_lshl_add_u64 v[176:177], s[0:1], 0, v[128:129]
	s_movk_i32 s0, 0x90
	v_or_b32_e32 v3, v153, v2
	v_lshl_or_b32 v9, v9, 6, v2
	v_readlane_b32 s9, v253, 39
	v_mul_lo_u32 v7, v152, s0
	v_mul_lo_u32 v3, v3, s0
	v_lshlrev_b32_e32 v10, 4, v6
	v_mul_lo_u32 v9, v9, s0
	v_readlane_b32 s0, v255, 15
	v_readlane_b32 s1, v255, 16
	v_lshl_add_u64 v[250:251], s[8:9], 0, v[128:129]
	v_add3_u32 v154, 0, v3, v10
	v_add_u32_e32 v13, s1, v7
	v_readlane_b32 s8, v255, 17
	v_add3_u32 v155, s0, v3, v10
	v_add_u32_e32 v3, s1, v9
	s_movk_i32 s1, 0x1200
	v_add_u32_e32 v14, s8, v7
	v_readlane_b32 s8, v255, 18
	v_mul_lo_u32 v1, v1, s1
	v_lshlrev_b32_e32 v5, 3, v4
	v_add_u32_e32 v12, s0, v7
	v_add_u32_e32 v15, s8, v7
	v_readlane_b32 s8, v255, 19
	v_add_u32_e32 v1, s0, v1
	v_lshlrev_b32_e32 v2, 1, v2
	v_mul_u32_u24_e32 v6, 0x240, v6
	v_bfe_u32 v157, v0, 3, 3
	s_movk_i32 s0, 0xffc0
	v_add_u32_e32 v4, 0, v128
	v_add_u32_e32 v11, 0, v9
	s_waitcnt vmcnt(3)
	v_add_u32_e32 v16, s8, v7
	v_add_u32_e32 v9, 0, v7
	v_add_u32_e32 v17, v1, v128
	v_add3_u32 v156, v1, v2, v6
	v_mul_u32_u24_e32 v1, 0x90, v157
	v_and_or_b32 v0, v0, s0, v5
	v_lshlrev_b32_e32 v2, 6, v8
	v_mov_b32_e32 v180, 0x2000
	v_or_b32_e32 v171, 8, v157
	v_or_b32_e32 v252, 16, v157
	v_or_b32_e32 v181, 24, v157
	v_sub_u32_e32 v179, v0, v2
	s_lshl_b32 s8, s4, 8
	s_lshl_b32 s9, s5, 8
	v_add_u32_e32 v162, v4, v7
	v_add_u32_e32 v163, v11, v10
	v_add_u32_e32 v164, v12, v128
	v_add_u32_e32 v165, v13, v128
	v_add_u32_e32 v166, v14, v128
	v_add_u32_e32 v167, v15, v128
	v_add_u32_e32 v168, v16, v128
	v_add_u32_e32 v169, v3, v10
	v_add_u32_e32 v128, v9, v128
	v_add_u32_e32 v170, v17, v1
	s_branch .Lgo_239

.Lgo_239:
	s_ashr_i32 s1, s4, 2
	s_add_i32 s0, s1, s7
	s_lshl_b32 s0, s0, 8
	v_add_u32_e32 v0, s0, v152
	v_ashrrev_i32_e32 v1, 31, v0
	v_lshlrev_b64 v[0:1], 11, v[0:1]
	s_mulk_i32 s1, 0xfc00
	v_lshl_add_u64 v[148:149], v[250:251], 0, v[0:1]
	s_add_i32 s1, s1, s8
	v_add_co_u32_e32 v150, vcc, 0x20000, v148
	v_add_u32_e32 v2, s1, v152
	s_nop 0
	v_addc_co_u32_e32 v151, vcc, 0, v149, vcc
	v_ashrrev_i32_e32 v3, 31, v2
	v_add_co_u32_e32 v144, vcc, 0x40000, v148
	v_lshlrev_b64 v[16:17], 11, v[2:3]
	s_nop 0
	v_addc_co_u32_e32 v145, vcc, 0, v149, vcc
	global_load_dwordx4 v[0:3], v[148:149], off
	v_add_co_u32_e32 v146, vcc, 0x60000, v148
	v_lshl_add_u64 v[140:141], v[176:177], 0, v[16:17]
	global_load_dwordx4 v[8:11], v[144:145], off
	global_load_dwordx4 v[16:19], v[140:141], off
	v_addc_co_u32_e32 v147, vcc, 0, v149, vcc
	global_load_dwordx4 v[4:7], v[150:151], off
	v_add_co_u32_e32 v138, vcc, s94, v140
	global_load_dwordx4 v[12:15], v[146:147], off
	s_nop 0
	v_addc_co_u32_e32 v139, vcc, 0, v141, vcc
	v_add_co_u32_e32 v134, vcc, 0x40000, v140
	global_load_dwordx4 v[20:23], v[138:139], off
	s_nop 0
	v_addc_co_u32_e32 v135, vcc, 0, v141, vcc
	global_load_dwordx4 v[24:27], v[134:135], off
	v_add_co_u32_e32 v136, vcc, s95, v140
	s_nop 1
	v_addc_co_u32_e32 v137, vcc, 0, v141, vcc
	global_load_dwordx4 v[28:31], v[136:137], off
	global_load_dwordx4 v[172:175], v[148:149], off offset:128
	global_load_dwordx4 v[182:185], v[150:151], off offset:128
	global_load_dwordx4 v[186:189], v[144:145], off offset:128
	global_load_dwordx4 v[190:193], v[146:147], off offset:128
	global_load_dwordx4 v[194:197], v[140:141], off offset:128
	global_load_dwordx4 v[198:201], v[138:139], off offset:128
	global_load_dwordx4 v[202:205], v[134:135], off offset:128
	global_load_dwordx4 v[206:209], v[136:137], off offset:128
	s_waitcnt vmcnt(15)
	ds_write_b128 v162, v[0:3]
	s_waitcnt vmcnt(13)
	ds_write_b128 v162, v[16:19] offset:36864
	s_waitcnt vmcnt(12)
	ds_write_b128 v162, v[4:7] offset:9216
	ds_write_b128 v162, v[8:11] offset:18432
	s_waitcnt vmcnt(11)
	ds_write_b128 v162, v[12:15] offset:27648
	s_waitcnt vmcnt(10)
	ds_write_b128 v162, v[20:23] offset:46080
	s_waitcnt vmcnt(9)
	ds_write_b128 v162, v[24:27] offset:55296
	s_waitcnt vmcnt(8)
	ds_write_b128 v162, v[28:31] offset:64512
	s_waitcnt lgkmcnt(0)
	s_barrier
	ds_read_b128 v[0:3], v163 offset:36864
	ds_read_b128 v[210:213], v163 offset:36896
	ds_read_b128 v[4:7], v163 offset:41472
	ds_read_b128 v[214:217], v163 offset:41504
	ds_read_b128 v[8:11], v154
	ds_read_b128 v[218:221], v154 offset:32
	ds_read_b128 v[12:15], v154 offset:4608
	ds_read_b128 v[222:225], v154 offset:4640
	ds_read_b128 v[16:19], v154 offset:9216
	ds_read_b128 v[226:229], v154 offset:9248
	ds_read_b128 v[230:233], v154 offset:13824
	ds_read_b128 v[234:237], v154 offset:13856
	s_waitcnt lgkmcnt(7)
	v_mfma_f32_32x32x16_bf16 v[112:127], v[8:11], v[0:3], 0
	v_mfma_f32_32x32x16_bf16 v[96:111], v[8:11], v[4:7], 0
	s_waitcnt lgkmcnt(5)
	v_mfma_f32_32x32x16_bf16 v[80:95], v[12:15], v[0:3], 0
	v_mfma_f32_32x32x16_bf16 v[64:79], v[12:15], v[4:7], 0
	s_waitcnt lgkmcnt(3)
	v_mfma_f32_32x32x16_bf16 v[48:63], v[16:19], v[0:3], 0
	v_mfma_f32_32x32x16_bf16 v[32:47], v[16:19], v[4:7], 0
	s_waitcnt lgkmcnt(1)
	v_mfma_f32_32x32x16_bf16 v[16:31], v[230:233], v[0:3], 0
	v_mfma_f32_32x32x16_bf16 v[0:15], v[230:233], v[4:7], 0
	global_load_dwordx4 v[230:233], v[148:149], off offset:256
	global_load_dwordx4 v[238:241], v[150:151], off offset:256
	s_waitcnt vmcnt(9)
	ds_write_b128 v164, v[172:175]
	s_waitcnt vmcnt(8)
	ds_write_b128 v164, v[182:185] offset:9216
	ds_read_b128 v[172:175], v163 offset:36928
	ds_read_b128 v[182:185], v163 offset:41536
	ds_read_b128 v[242:245], v154 offset:64
	ds_read_b128 v[246:249], v154 offset:4672
	ds_read_b128 v[130:133], v154 offset:9280
	ds_read_b128 v[158:161], v154 offset:13888
	v_mfma_f32_32x32x16_bf16 v[80:95], v[222:225], v[210:213], v[80:95]
	v_mfma_f32_32x32x16_bf16 v[64:79], v[222:225], v[214:217], v[64:79]
	v_mfma_f32_32x32x16_bf16 v[48:63], v[226:229], v[210:213], v[48:63]
	v_mfma_f32_32x32x16_bf16 v[32:47], v[226:229], v[214:217], v[32:47]
	s_waitcnt lgkmcnt(8)
	v_mfma_f32_32x32x16_bf16 v[16:31], v[234:237], v[210:213], v[16:31]
	v_mfma_f32_32x32x16_bf16 v[0:15], v[234:237], v[214:217], v[0:15]
	v_mfma_f32_32x32x16_bf16 v[112:127], v[218:221], v[210:213], v[112:127]
	v_mfma_f32_32x32x16_bf16 v[96:111], v[218:221], v[214:217], v[96:111]
	global_load_dwordx4 v[210:213], v[144:145], off offset:256
	global_load_dwordx4 v[214:217], v[146:147], off offset:256
	s_waitcnt vmcnt(9)
	ds_write_b128 v164, v[186:189] offset:18432
	s_waitcnt vmcnt(8)
	ds_write_b128 v164, v[190:193] offset:27648
	ds_read_b128 v[186:189], v163 offset:36960
	ds_read_b128 v[190:193], v163 offset:41568
	ds_read_b128 v[218:221], v154 offset:96
	ds_read_b128 v[222:225], v154 offset:4704
	ds_read_b128 v[226:229], v154 offset:9312
	ds_read_b128 v[234:237], v154 offset:13920
	s_waitcnt lgkmcnt(10)
	v_mfma_f32_32x32x16_bf16 v[80:95], v[246:249], v[172:175], v[80:95]
	v_mfma_f32_32x32x16_bf16 v[64:79], v[246:249], v[182:185], v[64:79]
	s_waitcnt lgkmcnt(9)
	v_mfma_f32_32x32x16_bf16 v[48:63], v[130:133], v[172:175], v[48:63]
	v_mfma_f32_32x32x16_bf16 v[32:47], v[130:133], v[182:185], v[32:47]
	s_waitcnt lgkmcnt(8)
	v_mfma_f32_32x32x16_bf16 v[16:31], v[158:161], v[172:175], v[16:31]
	v_mfma_f32_32x32x16_bf16 v[0:15], v[158:161], v[182:185], v[0:15]
	v_mfma_f32_32x32x16_bf16 v[112:127], v[242:245], v[172:175], v[112:127]
	v_mfma_f32_32x32x16_bf16 v[96:111], v[242:245], v[182:185], v[96:111]
	global_load_dwordx4 v[130:133], v[140:141], off offset:256
	global_load_dwordx4 v[158:161], v[138:139], off offset:256
	s_waitcnt vmcnt(9)
	ds_write_b128 v165, v[194:197]
	s_waitcnt vmcnt(8)
	ds_write_b128 v166, v[198:201]
	s_waitcnt lgkmcnt(4)
	v_mfma_f32_32x32x16_bf16 v[80:95], v[222:225], v[186:189], v[80:95]
	v_mfma_f32_32x32x16_bf16 v[64:79], v[222:225], v[190:193], v[64:79]
	s_waitcnt lgkmcnt(3)
	v_mfma_f32_32x32x16_bf16 v[48:63], v[226:229], v[186:189], v[48:63]
	v_mfma_f32_32x32x16_bf16 v[32:47], v[226:229], v[190:193], v[32:47]
	s_waitcnt lgkmcnt(2)
	v_mfma_f32_32x32x16_bf16 v[16:31], v[234:237], v[186:189], v[16:31]
	v_mfma_f32_32x32x16_bf16 v[0:15], v[234:237], v[190:193], v[0:15]
	v_mfma_f32_32x32x16_bf16 v[112:127], v[218:221], v[186:189], v[112:127]
	v_mfma_f32_32x32x16_bf16 v[96:111], v[218:221], v[190:193], v[96:111]
	global_load_dwordx4 v[172:175], v[134:135], off offset:256
	global_load_dwordx4 v[182:185], v[136:137], off offset:256
	s_waitcnt vmcnt(9)
	ds_write_b128 v167, v[202:205]
	s_waitcnt vmcnt(8)
	ds_write_b128 v168, v[206:209]
	s_waitcnt lgkmcnt(0)
	s_barrier
	ds_read_b128 v[186:189], v169
	ds_read_b128 v[190:193], v169 offset:32
	ds_read_b128 v[194:197], v169 offset:4608
	ds_read_b128 v[198:201], v169 offset:4640
	ds_read_b128 v[202:205], v155
	ds_read_b128 v[206:209], v155 offset:32
	ds_read_b128 v[218:221], v155 offset:4608
	ds_read_b128 v[222:225], v155 offset:4640
	ds_read_b128 v[226:229], v155 offset:9216
	ds_read_b128 v[234:237], v155 offset:9248
	ds_read_b128 v[242:245], v155 offset:13824
	ds_read_b128 v[246:249], v155 offset:13856
	s_waitcnt lgkmcnt(5)
	v_mfma_f32_32x32x16_bf16 v[80:95], v[218:221], v[186:189], v[80:95]
	v_mfma_f32_32x32x16_bf16 v[64:79], v[218:221], v[194:197], v[64:79]
	s_waitcnt lgkmcnt(3)
	v_mfma_f32_32x32x16_bf16 v[48:63], v[226:229], v[186:189], v[48:63]
	v_mfma_f32_32x32x16_bf16 v[32:47], v[226:229], v[194:197], v[32:47]
	s_waitcnt lgkmcnt(1)
	v_mfma_f32_32x32x16_bf16 v[16:31], v[242:245], v[186:189], v[16:31]
	v_mfma_f32_32x32x16_bf16 v[0:15], v[242:245], v[194:197], v[0:15]
	v_mfma_f32_32x32x16_bf16 v[112:127], v[202:205], v[186:189], v[112:127]
	v_mfma_f32_32x32x16_bf16 v[96:111], v[202:205], v[194:197], v[96:111]
	global_load_dwordx4 v[186:189], v[148:149], off offset:384
	global_load_dwordx4 v[194:197], v[150:151], off offset:384
	s_waitcnt vmcnt(9)
	ds_write_b128 v128, v[230:233]
	s_waitcnt vmcnt(8)
	ds_write_b128 v128, v[238:241] offset:9216
	ds_read_b128 v[202:205], v169 offset:64
	ds_read_b128 v[218:221], v169 offset:4672
	ds_read_b128 v[226:229], v155 offset:64
	ds_read_b128 v[230:233], v155 offset:4672
	ds_read_b128 v[238:241], v155 offset:9280
	ds_read_b128 v[242:245], v155 offset:13888
	v_mfma_f32_32x32x16_bf16 v[80:95], v[222:225], v[190:193], v[80:95]
	v_mfma_f32_32x32x16_bf16 v[64:79], v[222:225], v[198:201], v[64:79]
	v_mfma_f32_32x32x16_bf16 v[48:63], v[234:237], v[190:193], v[48:63]
	v_mfma_f32_32x32x16_bf16 v[32:47], v[234:237], v[198:201], v[32:47]
	s_waitcnt lgkmcnt(8)
	v_mfma_f32_32x32x16_bf16 v[16:31], v[246:249], v[190:193], v[16:31]
	v_mfma_f32_32x32x16_bf16 v[0:15], v[246:249], v[198:201], v[0:15]
	v_mfma_f32_32x32x16_bf16 v[112:127], v[206:209], v[190:193], v[112:127]
	v_mfma_f32_32x32x16_bf16 v[96:111], v[206:209], v[198:201], v[96:111]
	global_load_dwordx4 v[190:193], v[144:145], off offset:384
	global_load_dwordx4 v[198:201], v[146:147], off offset:384
	s_waitcnt vmcnt(9)
	ds_write_b128 v128, v[210:213] offset:18432
	s_waitcnt vmcnt(8)
	ds_write_b128 v128, v[214:217] offset:27648
	ds_read_b128 v[206:209], v169 offset:96
	ds_read_b128 v[210:213], v169 offset:4704
	ds_read_b128 v[214:217], v155 offset:96
	ds_read_b128 v[222:225], v155 offset:4704
	ds_read_b128 v[234:237], v155 offset:9312
	ds_read_b128 v[246:249], v155 offset:13920
	s_waitcnt lgkmcnt(10)
	v_mfma_f32_32x32x16_bf16 v[80:95], v[230:233], v[202:205], v[80:95]
	v_mfma_f32_32x32x16_bf16 v[64:79], v[230:233], v[218:221], v[64:79]
	s_waitcnt lgkmcnt(9)
	v_mfma_f32_32x32x16_bf16 v[48:63], v[238:241], v[202:205], v[48:63]
	v_mfma_f32_32x32x16_bf16 v[32:47], v[238:241], v[218:221], v[32:47]
	s_waitcnt lgkmcnt(8)
	v_mfma_f32_32x32x16_bf16 v[16:31], v[242:245], v[202:205], v[16:31]
	v_mfma_f32_32x32x16_bf16 v[0:15], v[242:245], v[218:221], v[0:15]
	v_mfma_f32_32x32x16_bf16 v[112:127], v[226:229], v[202:205], v[112:127]
	v_mfma_f32_32x32x16_bf16 v[96:111], v[226:229], v[218:221], v[96:111]
	s_waitcnt vmcnt(7)
	ds_write_b128 v128, v[130:133] offset:36864
	global_load_dwordx4 v[130:133], v[140:141], off offset:384
	s_waitcnt vmcnt(7)
	ds_write_b128 v128, v[158:161] offset:46080
	global_load_dwordx4 v[158:161], v[138:139], off offset:384
	s_waitcnt lgkmcnt(4)
	v_mfma_f32_32x32x16_bf16 v[80:95], v[222:225], v[206:209], v[80:95]
	v_mfma_f32_32x32x16_bf16 v[64:79], v[222:225], v[210:213], v[64:79]
	s_waitcnt lgkmcnt(3)
	v_mfma_f32_32x32x16_bf16 v[48:63], v[234:237], v[206:209], v[48:63]
	v_mfma_f32_32x32x16_bf16 v[32:47], v[234:237], v[210:213], v[32:47]
	s_waitcnt lgkmcnt(2)
	v_mfma_f32_32x32x16_bf16 v[16:31], v[246:249], v[206:209], v[16:31]
	v_mfma_f32_32x32x16_bf16 v[0:15], v[246:249], v[210:213], v[0:15]
	v_mfma_f32_32x32x16_bf16 v[112:127], v[214:217], v[206:209], v[112:127]
	v_mfma_f32_32x32x16_bf16 v[96:111], v[214:217], v[210:213], v[96:111]
	global_load_dwordx4 v[202:205], v[134:135], off offset:384
	global_load_dwordx4 v[206:209], v[136:137], off offset:384
	s_waitcnt vmcnt(9)
	ds_write_b128 v128, v[172:175] offset:55296
	s_waitcnt vmcnt(8)
	ds_write_b128 v128, v[182:185] offset:64512
	s_waitcnt lgkmcnt(0)
	s_barrier
	ds_read_b128 v[172:175], v163 offset:36864
	ds_read_b128 v[182:185], v163 offset:36896
	ds_read_b128 v[210:213], v163 offset:41472
	ds_read_b128 v[214:217], v163 offset:41504
	ds_read_b128 v[218:221], v154
	ds_read_b128 v[222:225], v154 offset:32
	ds_read_b128 v[226:229], v154 offset:4608
	ds_read_b128 v[230:233], v154 offset:4640
	ds_read_b128 v[234:237], v154 offset:9216
	ds_read_b128 v[238:241], v154 offset:9248
	ds_read_b128 v[242:245], v154 offset:13824
	ds_read_b128 v[246:249], v154 offset:13856
	s_waitcnt lgkmcnt(5)
	v_mfma_f32_32x32x16_bf16 v[80:95], v[226:229], v[172:175], v[80:95]
	v_mfma_f32_32x32x16_bf16 v[64:79], v[226:229], v[210:213], v[64:79]
	s_waitcnt lgkmcnt(3)
	v_mfma_f32_32x32x16_bf16 v[48:63], v[234:237], v[172:175], v[48:63]
	v_mfma_f32_32x32x16_bf16 v[32:47], v[234:237], v[210:213], v[32:47]
	s_waitcnt lgkmcnt(1)
	v_mfma_f32_32x32x16_bf16 v[16:31], v[242:245], v[172:175], v[16:31]
	v_mfma_f32_32x32x16_bf16 v[0:15], v[242:245], v[210:213], v[0:15]
	v_mfma_f32_32x32x16_bf16 v[112:127], v[218:221], v[172:175], v[112:127]
	v_mfma_f32_32x32x16_bf16 v[96:111], v[218:221], v[210:213], v[96:111]
	global_load_dwordx4 v[172:175], v[148:149], off offset:512
	global_load_dwordx4 v[210:213], v[150:151], off offset:512
	s_waitcnt vmcnt(9)
	ds_write_b128 v164, v[186:189]
	s_waitcnt vmcnt(8)
	ds_write_b128 v164, v[194:197] offset:9216
	ds_read_b128 v[186:189], v163 offset:36928
	ds_read_b128 v[194:197], v163 offset:41536
	ds_read_b128 v[218:221], v154 offset:64
	ds_read_b128 v[226:229], v154 offset:4672
	ds_read_b128 v[234:237], v154 offset:9280
	ds_read_b128 v[242:245], v154 offset:13888
	v_mfma_f32_32x32x16_bf16 v[80:95], v[230:233], v[182:185], v[80:95]
	v_mfma_f32_32x32x16_bf16 v[64:79], v[230:233], v[214:217], v[64:79]
	v_mfma_f32_32x32x16_bf16 v[48:63], v[238:241], v[182:185], v[48:63]
	v_mfma_f32_32x32x16_bf16 v[32:47], v[238:241], v[214:217], v[32:47]
	s_waitcnt lgkmcnt(8)
	v_mfma_f32_32x32x16_bf16 v[16:31], v[246:249], v[182:185], v[16:31]
	v_mfma_f32_32x32x16_bf16 v[0:15], v[246:249], v[214:217], v[0:15]
	v_mfma_f32_32x32x16_bf16 v[112:127], v[222:225], v[182:185], v[112:127]
	v_mfma_f32_32x32x16_bf16 v[96:111], v[222:225], v[214:217], v[96:111]
	global_load_dwordx4 v[182:185], v[144:145], off offset:512
	global_load_dwordx4 v[214:217], v[146:147], off offset:512
	s_waitcnt vmcnt(9)
	ds_write_b128 v164, v[190:193] offset:18432
	s_waitcnt vmcnt(8)
	ds_write_b128 v164, v[198:201] offset:27648
	ds_read_b128 v[190:193], v163 offset:36960
	ds_read_b128 v[198:201], v163 offset:41568
	ds_read_b128 v[222:225], v154 offset:96
	ds_read_b128 v[230:233], v154 offset:4704
	ds_read_b128 v[238:241], v154 offset:9312
	ds_read_b128 v[246:249], v154 offset:13920
	s_waitcnt lgkmcnt(10)
	v_mfma_f32_32x32x16_bf16 v[80:95], v[226:229], v[186:189], v[80:95]
	v_mfma_f32_32x32x16_bf16 v[64:79], v[226:229], v[194:197], v[64:79]
	s_waitcnt lgkmcnt(9)
	v_mfma_f32_32x32x16_bf16 v[48:63], v[234:237], v[186:189], v[48:63]
	v_mfma_f32_32x32x16_bf16 v[32:47], v[234:237], v[194:197], v[32:47]
	s_waitcnt lgkmcnt(8)
	v_mfma_f32_32x32x16_bf16 v[16:31], v[242:245], v[186:189], v[16:31]
	v_mfma_f32_32x32x16_bf16 v[0:15], v[242:245], v[194:197], v[0:15]
	v_mfma_f32_32x32x16_bf16 v[112:127], v[218:221], v[186:189], v[112:127]
	v_mfma_f32_32x32x16_bf16 v[96:111], v[218:221], v[194:197], v[96:111]
	s_waitcnt vmcnt(7)
	ds_write_b128 v165, v[130:133]
	global_load_dwordx4 v[130:133], v[140:141], off offset:512
	s_waitcnt vmcnt(7)
	ds_write_b128 v166, v[158:161]
	global_load_dwordx4 v[158:161], v[138:139], off offset:512
	s_waitcnt lgkmcnt(4)
	v_mfma_f32_32x32x16_bf16 v[80:95], v[230:233], v[190:193], v[80:95]
	v_mfma_f32_32x32x16_bf16 v[64:79], v[230:233], v[198:201], v[64:79]
	s_waitcnt lgkmcnt(3)
	v_mfma_f32_32x32x16_bf16 v[48:63], v[238:241], v[190:193], v[48:63]
	v_mfma_f32_32x32x16_bf16 v[32:47], v[238:241], v[198:201], v[32:47]
	s_waitcnt lgkmcnt(2)
	v_mfma_f32_32x32x16_bf16 v[16:31], v[246:249], v[190:193], v[16:31]
	v_mfma_f32_32x32x16_bf16 v[0:15], v[246:249], v[198:201], v[0:15]
	v_mfma_f32_32x32x16_bf16 v[112:127], v[222:225], v[190:193], v[112:127]
	v_mfma_f32_32x32x16_bf16 v[96:111], v[222:225], v[198:201], v[96:111]
	global_load_dwordx4 v[186:189], v[134:135], off offset:512
	global_load_dwordx4 v[190:193], v[136:137], off offset:512
	s_waitcnt vmcnt(9)
	ds_write_b128 v167, v[202:205]
	s_waitcnt vmcnt(8)
	ds_write_b128 v168, v[206:209]
	s_waitcnt lgkmcnt(0)
	s_barrier
	ds_read_b128 v[194:197], v169
	ds_read_b128 v[198:201], v169 offset:32
	ds_read_b128 v[202:205], v169 offset:4608
	ds_read_b128 v[206:209], v169 offset:4640
	ds_read_b128 v[218:221], v155
	ds_read_b128 v[222:225], v155 offset:32
	ds_read_b128 v[226:229], v155 offset:4608
	ds_read_b128 v[230:233], v155 offset:4640
	ds_read_b128 v[234:237], v155 offset:9216
	ds_read_b128 v[238:241], v155 offset:9248
	ds_read_b128 v[242:245], v155 offset:13824
	ds_read_b128 v[246:249], v155 offset:13856
	s_waitcnt lgkmcnt(5)
	v_mfma_f32_32x32x16_bf16 v[80:95], v[226:229], v[194:197], v[80:95]
	v_mfma_f32_32x32x16_bf16 v[64:79], v[226:229], v[202:205], v[64:79]
	s_waitcnt lgkmcnt(3)
	v_mfma_f32_32x32x16_bf16 v[48:63], v[234:237], v[194:197], v[48:63]
	v_mfma_f32_32x32x16_bf16 v[32:47], v[234:237], v[202:205], v[32:47]
	s_waitcnt lgkmcnt(1)
	v_mfma_f32_32x32x16_bf16 v[16:31], v[242:245], v[194:197], v[16:31]
	v_mfma_f32_32x32x16_bf16 v[0:15], v[242:245], v[202:205], v[0:15]
	v_mfma_f32_32x32x16_bf16 v[112:127], v[218:221], v[194:197], v[112:127]
	v_mfma_f32_32x32x16_bf16 v[96:111], v[218:221], v[202:205], v[96:111]
	global_load_dwordx4 v[194:197], v[148:149], off offset:640
	global_load_dwordx4 v[202:205], v[150:151], off offset:640
	s_waitcnt vmcnt(9)
	ds_write_b128 v128, v[172:175]
	s_waitcnt vmcnt(8)
	ds_write_b128 v128, v[210:213] offset:9216
	ds_read_b128 v[172:175], v169 offset:64
	ds_read_b128 v[210:213], v169 offset:4672
	ds_read_b128 v[218:221], v155 offset:64
	ds_read_b128 v[226:229], v155 offset:4672
	ds_read_b128 v[234:237], v155 offset:9280
	ds_read_b128 v[242:245], v155 offset:13888
	v_mfma_f32_32x32x16_bf16 v[80:95], v[230:233], v[198:201], v[80:95]
	v_mfma_f32_32x32x16_bf16 v[64:79], v[230:233], v[206:209], v[64:79]
	v_mfma_f32_32x32x16_bf16 v[48:63], v[238:241], v[198:201], v[48:63]
	v_mfma_f32_32x32x16_bf16 v[32:47], v[238:241], v[206:209], v[32:47]
	s_waitcnt lgkmcnt(8)
	v_mfma_f32_32x32x16_bf16 v[16:31], v[246:249], v[198:201], v[16:31]
	v_mfma_f32_32x32x16_bf16 v[0:15], v[246:249], v[206:209], v[0:15]
	v_mfma_f32_32x32x16_bf16 v[112:127], v[222:225], v[198:201], v[112:127]
	v_mfma_f32_32x32x16_bf16 v[96:111], v[222:225], v[206:209], v[96:111]
	global_load_dwordx4 v[198:201], v[144:145], off offset:640
	global_load_dwordx4 v[206:209], v[146:147], off offset:640
	s_waitcnt vmcnt(9)
	ds_write_b128 v128, v[182:185] offset:18432
	s_waitcnt vmcnt(8)
	ds_write_b128 v128, v[214:217] offset:27648
	ds_read_b128 v[182:185], v169 offset:96
	ds_read_b128 v[214:217], v169 offset:4704
	ds_read_b128 v[222:225], v155 offset:96
	ds_read_b128 v[230:233], v155 offset:4704
	ds_read_b128 v[238:241], v155 offset:9312
	ds_read_b128 v[246:249], v155 offset:13920
	s_waitcnt lgkmcnt(10)
	v_mfma_f32_32x32x16_bf16 v[80:95], v[226:229], v[172:175], v[80:95]
	v_mfma_f32_32x32x16_bf16 v[64:79], v[226:229], v[210:213], v[64:79]
	s_waitcnt lgkmcnt(9)
	v_mfma_f32_32x32x16_bf16 v[48:63], v[234:237], v[172:175], v[48:63]
	v_mfma_f32_32x32x16_bf16 v[32:47], v[234:237], v[210:213], v[32:47]
	s_waitcnt lgkmcnt(8)
	v_mfma_f32_32x32x16_bf16 v[16:31], v[242:245], v[172:175], v[16:31]
	v_mfma_f32_32x32x16_bf16 v[0:15], v[242:245], v[210:213], v[0:15]
	v_mfma_f32_32x32x16_bf16 v[112:127], v[218:221], v[172:175], v[112:127]
	v_mfma_f32_32x32x16_bf16 v[96:111], v[218:221], v[210:213], v[96:111]
	s_waitcnt vmcnt(7)
	ds_write_b128 v128, v[130:133] offset:36864
	global_load_dwordx4 v[130:133], v[140:141], off offset:640
	s_waitcnt vmcnt(7)
	ds_write_b128 v128, v[158:161] offset:46080
	global_load_dwordx4 v[158:161], v[138:139], off offset:640
	s_waitcnt lgkmcnt(4)
	v_mfma_f32_32x32x16_bf16 v[80:95], v[230:233], v[182:185], v[80:95]
	v_mfma_f32_32x32x16_bf16 v[64:79], v[230:233], v[214:217], v[64:79]
	s_waitcnt lgkmcnt(3)
	v_mfma_f32_32x32x16_bf16 v[48:63], v[238:241], v[182:185], v[48:63]
	v_mfma_f32_32x32x16_bf16 v[32:47], v[238:241], v[214:217], v[32:47]
	s_waitcnt lgkmcnt(2)
	v_mfma_f32_32x32x16_bf16 v[16:31], v[246:249], v[182:185], v[16:31]
	v_mfma_f32_32x32x16_bf16 v[0:15], v[246:249], v[214:217], v[0:15]
	v_mfma_f32_32x32x16_bf16 v[112:127], v[222:225], v[182:185], v[112:127]
	v_mfma_f32_32x32x16_bf16 v[96:111], v[222:225], v[214:217], v[96:111]
	global_load_dwordx4 v[172:175], v[134:135], off offset:640
	global_load_dwordx4 v[182:185], v[136:137], off offset:640
	s_waitcnt vmcnt(9)
	ds_write_b128 v128, v[186:189] offset:55296
	s_waitcnt vmcnt(8)
	ds_write_b128 v128, v[190:193] offset:64512
	s_waitcnt lgkmcnt(0)
	s_barrier
	ds_read_b128 v[186:189], v163 offset:36864
	ds_read_b128 v[190:193], v163 offset:36896
	ds_read_b128 v[210:213], v163 offset:41472
	ds_read_b128 v[214:217], v163 offset:41504
	ds_read_b128 v[218:221], v154
	ds_read_b128 v[222:225], v154 offset:32
	ds_read_b128 v[226:229], v154 offset:4608
	ds_read_b128 v[230:233], v154 offset:4640
	ds_read_b128 v[234:237], v154 offset:9216
	ds_read_b128 v[238:241], v154 offset:9248
	ds_read_b128 v[242:245], v154 offset:13824
	ds_read_b128 v[246:249], v154 offset:13856
	s_waitcnt lgkmcnt(5)
	v_mfma_f32_32x32x16_bf16 v[80:95], v[226:229], v[186:189], v[80:95]
	v_mfma_f32_32x32x16_bf16 v[64:79], v[226:229], v[210:213], v[64:79]
	s_waitcnt lgkmcnt(3)
	v_mfma_f32_32x32x16_bf16 v[48:63], v[234:237], v[186:189], v[48:63]
	v_mfma_f32_32x32x16_bf16 v[32:47], v[234:237], v[210:213], v[32:47]
	s_waitcnt lgkmcnt(1)
	v_mfma_f32_32x32x16_bf16 v[16:31], v[242:245], v[186:189], v[16:31]
	v_mfma_f32_32x32x16_bf16 v[0:15], v[242:245], v[210:213], v[0:15]
	v_mfma_f32_32x32x16_bf16 v[112:127], v[218:221], v[186:189], v[112:127]
	v_mfma_f32_32x32x16_bf16 v[96:111], v[218:221], v[210:213], v[96:111]
	global_load_dwordx4 v[186:189], v[148:149], off offset:768
	global_load_dwordx4 v[210:213], v[150:151], off offset:768
	s_waitcnt vmcnt(9)
	ds_write_b128 v164, v[194:197]
	s_waitcnt vmcnt(8)
	ds_write_b128 v164, v[202:205] offset:9216
	ds_read_b128 v[194:197], v163 offset:36928
	ds_read_b128 v[202:205], v163 offset:41536
	ds_read_b128 v[218:221], v154 offset:64
	ds_read_b128 v[226:229], v154 offset:4672
	ds_read_b128 v[234:237], v154 offset:9280
	ds_read_b128 v[242:245], v154 offset:13888
	v_mfma_f32_32x32x16_bf16 v[80:95], v[230:233], v[190:193], v[80:95]
	v_mfma_f32_32x32x16_bf16 v[64:79], v[230:233], v[214:217], v[64:79]
	v_mfma_f32_32x32x16_bf16 v[48:63], v[238:241], v[190:193], v[48:63]
	v_mfma_f32_32x32x16_bf16 v[32:47], v[238:241], v[214:217], v[32:47]
	s_waitcnt lgkmcnt(8)
	v_mfma_f32_32x32x16_bf16 v[16:31], v[246:249], v[190:193], v[16:31]
	v_mfma_f32_32x32x16_bf16 v[0:15], v[246:249], v[214:217], v[0:15]
	v_mfma_f32_32x32x16_bf16 v[112:127], v[222:225], v[190:193], v[112:127]
	v_mfma_f32_32x32x16_bf16 v[96:111], v[222:225], v[214:217], v[96:111]
	global_load_dwordx4 v[190:193], v[144:145], off offset:768
	global_load_dwordx4 v[214:217], v[146:147], off offset:768
	s_waitcnt vmcnt(9)
	ds_write_b128 v164, v[198:201] offset:18432
	s_waitcnt vmcnt(8)
	ds_write_b128 v164, v[206:209] offset:27648
	ds_read_b128 v[198:201], v163 offset:36960
	ds_read_b128 v[206:209], v163 offset:41568
	ds_read_b128 v[222:225], v154 offset:96
	ds_read_b128 v[230:233], v154 offset:4704
	ds_read_b128 v[238:241], v154 offset:9312
	ds_read_b128 v[246:249], v154 offset:13920
	s_waitcnt lgkmcnt(10)
	v_mfma_f32_32x32x16_bf16 v[80:95], v[226:229], v[194:197], v[80:95]
	v_mfma_f32_32x32x16_bf16 v[64:79], v[226:229], v[202:205], v[64:79]
	s_waitcnt lgkmcnt(9)
	v_mfma_f32_32x32x16_bf16 v[48:63], v[234:237], v[194:197], v[48:63]
	v_mfma_f32_32x32x16_bf16 v[32:47], v[234:237], v[202:205], v[32:47]
	s_waitcnt lgkmcnt(8)
	v_mfma_f32_32x32x16_bf16 v[16:31], v[242:245], v[194:197], v[16:31]
	v_mfma_f32_32x32x16_bf16 v[0:15], v[242:245], v[202:205], v[0:15]
	v_mfma_f32_32x32x16_bf16 v[112:127], v[218:221], v[194:197], v[112:127]
	v_mfma_f32_32x32x16_bf16 v[96:111], v[218:221], v[202:205], v[96:111]
	s_waitcnt vmcnt(7)
	ds_write_b128 v165, v[130:133]
	global_load_dwordx4 v[130:133], v[140:141], off offset:768
	s_waitcnt vmcnt(7)
	ds_write_b128 v166, v[158:161]
	global_load_dwordx4 v[158:161], v[138:139], off offset:768
	s_waitcnt lgkmcnt(4)
	v_mfma_f32_32x32x16_bf16 v[80:95], v[230:233], v[198:201], v[80:95]
	v_mfma_f32_32x32x16_bf16 v[64:79], v[230:233], v[206:209], v[64:79]
	s_waitcnt lgkmcnt(3)
	v_mfma_f32_32x32x16_bf16 v[48:63], v[238:241], v[198:201], v[48:63]
	v_mfma_f32_32x32x16_bf16 v[32:47], v[238:241], v[206:209], v[32:47]
	s_waitcnt lgkmcnt(2)
	v_mfma_f32_32x32x16_bf16 v[16:31], v[246:249], v[198:201], v[16:31]
	v_mfma_f32_32x32x16_bf16 v[0:15], v[246:249], v[206:209], v[0:15]
	v_mfma_f32_32x32x16_bf16 v[112:127], v[222:225], v[198:201], v[112:127]
	v_mfma_f32_32x32x16_bf16 v[96:111], v[222:225], v[206:209], v[96:111]
	global_load_dwordx4 v[194:197], v[134:135], off offset:768
	global_load_dwordx4 v[198:201], v[136:137], off offset:768
	s_waitcnt vmcnt(9)
	ds_write_b128 v167, v[172:175]
	s_waitcnt vmcnt(8)
	ds_write_b128 v168, v[182:185]
	s_waitcnt lgkmcnt(0)
	s_barrier
	ds_read_b128 v[172:175], v169
	ds_read_b128 v[182:185], v169 offset:32
	ds_read_b128 v[202:205], v169 offset:4608
	ds_read_b128 v[206:209], v169 offset:4640
	ds_read_b128 v[218:221], v155
	ds_read_b128 v[222:225], v155 offset:32
	ds_read_b128 v[226:229], v155 offset:4608
	ds_read_b128 v[230:233], v155 offset:4640
	ds_read_b128 v[234:237], v155 offset:9216
	ds_read_b128 v[238:241], v155 offset:9248
	ds_read_b128 v[242:245], v155 offset:13824
	ds_read_b128 v[246:249], v155 offset:13856
	s_waitcnt lgkmcnt(5)
	v_mfma_f32_32x32x16_bf16 v[80:95], v[226:229], v[172:175], v[80:95]
	v_mfma_f32_32x32x16_bf16 v[64:79], v[226:229], v[202:205], v[64:79]
	s_waitcnt lgkmcnt(3)
	v_mfma_f32_32x32x16_bf16 v[48:63], v[234:237], v[172:175], v[48:63]
	v_mfma_f32_32x32x16_bf16 v[32:47], v[234:237], v[202:205], v[32:47]
	s_waitcnt lgkmcnt(1)
	v_mfma_f32_32x32x16_bf16 v[16:31], v[242:245], v[172:175], v[16:31]
	v_mfma_f32_32x32x16_bf16 v[0:15], v[242:245], v[202:205], v[0:15]
	v_mfma_f32_32x32x16_bf16 v[112:127], v[218:221], v[172:175], v[112:127]
	v_mfma_f32_32x32x16_bf16 v[96:111], v[218:221], v[202:205], v[96:111]
	global_load_dwordx4 v[172:175], v[148:149], off offset:896
	global_load_dwordx4 v[202:205], v[150:151], off offset:896
	s_waitcnt vmcnt(9)
	ds_write_b128 v128, v[186:189]
	s_waitcnt vmcnt(8)
	ds_write_b128 v128, v[210:213] offset:9216
	ds_read_b128 v[186:189], v169 offset:64
	ds_read_b128 v[210:213], v169 offset:4672
	ds_read_b128 v[218:221], v155 offset:64
	ds_read_b128 v[226:229], v155 offset:4672
	ds_read_b128 v[234:237], v155 offset:9280
	ds_read_b128 v[242:245], v155 offset:13888
	v_mfma_f32_32x32x16_bf16 v[80:95], v[230:233], v[182:185], v[80:95]
	v_mfma_f32_32x32x16_bf16 v[64:79], v[230:233], v[206:209], v[64:79]
	v_mfma_f32_32x32x16_bf16 v[48:63], v[238:241], v[182:185], v[48:63]
	v_mfma_f32_32x32x16_bf16 v[32:47], v[238:241], v[206:209], v[32:47]
	s_waitcnt lgkmcnt(8)
	v_mfma_f32_32x32x16_bf16 v[16:31], v[246:249], v[182:185], v[16:31]
	v_mfma_f32_32x32x16_bf16 v[0:15], v[246:249], v[206:209], v[0:15]
	v_mfma_f32_32x32x16_bf16 v[112:127], v[222:225], v[182:185], v[112:127]
	v_mfma_f32_32x32x16_bf16 v[96:111], v[222:225], v[206:209], v[96:111]
	global_load_dwordx4 v[182:185], v[144:145], off offset:896
	global_load_dwordx4 v[206:209], v[146:147], off offset:896
	s_waitcnt vmcnt(9)
	ds_write_b128 v128, v[190:193] offset:18432
	s_waitcnt vmcnt(8)
	ds_write_b128 v128, v[214:217] offset:27648
	ds_read_b128 v[190:193], v169 offset:96
	ds_read_b128 v[214:217], v169 offset:4704
	ds_read_b128 v[222:225], v155 offset:96
	ds_read_b128 v[230:233], v155 offset:4704
	ds_read_b128 v[238:241], v155 offset:9312
	ds_read_b128 v[246:249], v155 offset:13920
	s_waitcnt lgkmcnt(10)
	v_mfma_f32_32x32x16_bf16 v[80:95], v[226:229], v[186:189], v[80:95]
	v_mfma_f32_32x32x16_bf16 v[64:79], v[226:229], v[210:213], v[64:79]
	s_waitcnt lgkmcnt(9)
	v_mfma_f32_32x32x16_bf16 v[48:63], v[234:237], v[186:189], v[48:63]
	v_mfma_f32_32x32x16_bf16 v[32:47], v[234:237], v[210:213], v[32:47]
	s_waitcnt lgkmcnt(8)
	v_mfma_f32_32x32x16_bf16 v[16:31], v[242:245], v[186:189], v[16:31]
	v_mfma_f32_32x32x16_bf16 v[0:15], v[242:245], v[210:213], v[0:15]
	v_mfma_f32_32x32x16_bf16 v[112:127], v[218:221], v[186:189], v[112:127]
	v_mfma_f32_32x32x16_bf16 v[96:111], v[218:221], v[210:213], v[96:111]
	s_waitcnt vmcnt(7)
	ds_write_b128 v128, v[130:133] offset:36864
	global_load_dwordx4 v[130:133], v[140:141], off offset:896
	s_waitcnt vmcnt(7)
	ds_write_b128 v128, v[158:161] offset:46080
	global_load_dwordx4 v[158:161], v[138:139], off offset:896
	s_waitcnt lgkmcnt(4)
	v_mfma_f32_32x32x16_bf16 v[80:95], v[230:233], v[190:193], v[80:95]
	v_mfma_f32_32x32x16_bf16 v[64:79], v[230:233], v[214:217], v[64:79]
	s_waitcnt lgkmcnt(3)
	v_mfma_f32_32x32x16_bf16 v[48:63], v[238:241], v[190:193], v[48:63]
	v_mfma_f32_32x32x16_bf16 v[32:47], v[238:241], v[214:217], v[32:47]
	s_waitcnt lgkmcnt(2)
	v_mfma_f32_32x32x16_bf16 v[16:31], v[246:249], v[190:193], v[16:31]
	v_mfma_f32_32x32x16_bf16 v[0:15], v[246:249], v[214:217], v[0:15]
	v_mfma_f32_32x32x16_bf16 v[112:127], v[222:225], v[190:193], v[112:127]
	v_mfma_f32_32x32x16_bf16 v[96:111], v[222:225], v[214:217], v[96:111]
	global_load_dwordx4 v[186:189], v[134:135], off offset:896
	global_load_dwordx4 v[190:193], v[136:137], off offset:896
	s_waitcnt vmcnt(9)
	ds_write_b128 v128, v[194:197] offset:55296
	s_waitcnt vmcnt(8)
	ds_write_b128 v128, v[198:201] offset:64512
	s_waitcnt lgkmcnt(0)
	s_barrier
	ds_read_b128 v[194:197], v163 offset:36864
	ds_read_b128 v[198:201], v163 offset:36896
	ds_read_b128 v[210:213], v163 offset:41472
	ds_read_b128 v[214:217], v163 offset:41504
	ds_read_b128 v[218:221], v154
	ds_read_b128 v[222:225], v154 offset:32
	ds_read_b128 v[226:229], v154 offset:4608
	ds_read_b128 v[230:233], v154 offset:4640
	ds_read_b128 v[234:237], v154 offset:9216
	ds_read_b128 v[238:241], v154 offset:9248
	ds_read_b128 v[242:245], v154 offset:13824
	ds_read_b128 v[246:249], v154 offset:13856
	s_waitcnt lgkmcnt(5)
	v_mfma_f32_32x32x16_bf16 v[80:95], v[226:229], v[194:197], v[80:95]
	v_mfma_f32_32x32x16_bf16 v[64:79], v[226:229], v[210:213], v[64:79]
	s_waitcnt lgkmcnt(3)
	v_mfma_f32_32x32x16_bf16 v[48:63], v[234:237], v[194:197], v[48:63]
	v_mfma_f32_32x32x16_bf16 v[32:47], v[234:237], v[210:213], v[32:47]
	s_waitcnt lgkmcnt(1)
	v_mfma_f32_32x32x16_bf16 v[16:31], v[242:245], v[194:197], v[16:31]
	v_mfma_f32_32x32x16_bf16 v[0:15], v[242:245], v[210:213], v[0:15]
	v_mfma_f32_32x32x16_bf16 v[112:127], v[218:221], v[194:197], v[112:127]
	v_mfma_f32_32x32x16_bf16 v[96:111], v[218:221], v[210:213], v[96:111]
	global_load_dwordx4 v[194:197], v[148:149], off offset:1024
	global_load_dwordx4 v[210:213], v[150:151], off offset:1024
	s_waitcnt vmcnt(9)
	ds_write_b128 v164, v[172:175]
	s_waitcnt vmcnt(8)
	ds_write_b128 v164, v[202:205] offset:9216
	ds_read_b128 v[172:175], v163 offset:36928
	ds_read_b128 v[202:205], v163 offset:41536
	ds_read_b128 v[218:221], v154 offset:64
	ds_read_b128 v[226:229], v154 offset:4672
	ds_read_b128 v[234:237], v154 offset:9280
	ds_read_b128 v[242:245], v154 offset:13888
	v_mfma_f32_32x32x16_bf16 v[80:95], v[230:233], v[198:201], v[80:95]
	v_mfma_f32_32x32x16_bf16 v[64:79], v[230:233], v[214:217], v[64:79]
	v_mfma_f32_32x32x16_bf16 v[48:63], v[238:241], v[198:201], v[48:63]
	v_mfma_f32_32x32x16_bf16 v[32:47], v[238:241], v[214:217], v[32:47]
	s_waitcnt lgkmcnt(8)
	v_mfma_f32_32x32x16_bf16 v[16:31], v[246:249], v[198:201], v[16:31]
	v_mfma_f32_32x32x16_bf16 v[0:15], v[246:249], v[214:217], v[0:15]
	v_mfma_f32_32x32x16_bf16 v[112:127], v[222:225], v[198:201], v[112:127]
	v_mfma_f32_32x32x16_bf16 v[96:111], v[222:225], v[214:217], v[96:111]
	global_load_dwordx4 v[198:201], v[144:145], off offset:1024
	global_load_dwordx4 v[214:217], v[146:147], off offset:1024
	s_waitcnt vmcnt(9)
	ds_write_b128 v164, v[182:185] offset:18432
	s_waitcnt vmcnt(8)
	ds_write_b128 v164, v[206:209] offset:27648
	ds_read_b128 v[182:185], v163 offset:36960
	ds_read_b128 v[206:209], v163 offset:41568
	ds_read_b128 v[222:225], v154 offset:96
	ds_read_b128 v[230:233], v154 offset:4704
	ds_read_b128 v[238:241], v154 offset:9312
	ds_read_b128 v[246:249], v154 offset:13920
	s_waitcnt lgkmcnt(10)
	v_mfma_f32_32x32x16_bf16 v[80:95], v[226:229], v[172:175], v[80:95]
	v_mfma_f32_32x32x16_bf16 v[64:79], v[226:229], v[202:205], v[64:79]
	s_waitcnt lgkmcnt(9)
	v_mfma_f32_32x32x16_bf16 v[48:63], v[234:237], v[172:175], v[48:63]
	v_mfma_f32_32x32x16_bf16 v[32:47], v[234:237], v[202:205], v[32:47]
	s_waitcnt lgkmcnt(8)
	v_mfma_f32_32x32x16_bf16 v[16:31], v[242:245], v[172:175], v[16:31]
	v_mfma_f32_32x32x16_bf16 v[0:15], v[242:245], v[202:205], v[0:15]
	v_mfma_f32_32x32x16_bf16 v[112:127], v[218:221], v[172:175], v[112:127]
	v_mfma_f32_32x32x16_bf16 v[96:111], v[218:221], v[202:205], v[96:111]
	s_waitcnt vmcnt(7)
	ds_write_b128 v165, v[130:133]
	global_load_dwordx4 v[130:133], v[140:141], off offset:1024
	s_waitcnt vmcnt(7)
	ds_write_b128 v166, v[158:161]
	global_load_dwordx4 v[158:161], v[138:139], off offset:1024
	s_waitcnt lgkmcnt(4)
	v_mfma_f32_32x32x16_bf16 v[80:95], v[230:233], v[182:185], v[80:95]
	v_mfma_f32_32x32x16_bf16 v[64:79], v[230:233], v[206:209], v[64:79]
	s_waitcnt lgkmcnt(3)
	v_mfma_f32_32x32x16_bf16 v[48:63], v[238:241], v[182:185], v[48:63]
	v_mfma_f32_32x32x16_bf16 v[32:47], v[238:241], v[206:209], v[32:47]
	s_waitcnt lgkmcnt(2)
	v_mfma_f32_32x32x16_bf16 v[16:31], v[246:249], v[182:185], v[16:31]
	v_mfma_f32_32x32x16_bf16 v[0:15], v[246:249], v[206:209], v[0:15]
	v_mfma_f32_32x32x16_bf16 v[112:127], v[222:225], v[182:185], v[112:127]
	v_mfma_f32_32x32x16_bf16 v[96:111], v[222:225], v[206:209], v[96:111]
	global_load_dwordx4 v[172:175], v[134:135], off offset:1024
	global_load_dwordx4 v[182:185], v[136:137], off offset:1024
	s_waitcnt vmcnt(9)
	ds_write_b128 v167, v[186:189]
	s_waitcnt vmcnt(8)
	ds_write_b128 v168, v[190:193]
	s_waitcnt lgkmcnt(0)
	s_barrier
	ds_read_b128 v[186:189], v169
	ds_read_b128 v[190:193], v169 offset:32
	ds_read_b128 v[202:205], v169 offset:4608
	ds_read_b128 v[206:209], v169 offset:4640
	ds_read_b128 v[218:221], v155
	ds_read_b128 v[222:225], v155 offset:32
	ds_read_b128 v[226:229], v155 offset:4608
	ds_read_b128 v[230:233], v155 offset:4640
	ds_read_b128 v[234:237], v155 offset:9216
	ds_read_b128 v[238:241], v155 offset:9248
	ds_read_b128 v[242:245], v155 offset:13824
	ds_read_b128 v[246:249], v155 offset:13856
	s_waitcnt lgkmcnt(5)
	v_mfma_f32_32x32x16_bf16 v[80:95], v[226:229], v[186:189], v[80:95]
	v_mfma_f32_32x32x16_bf16 v[64:79], v[226:229], v[202:205], v[64:79]
	s_waitcnt lgkmcnt(3)
	v_mfma_f32_32x32x16_bf16 v[48:63], v[234:237], v[186:189], v[48:63]
	v_mfma_f32_32x32x16_bf16 v[32:47], v[234:237], v[202:205], v[32:47]
	s_waitcnt lgkmcnt(1)
	v_mfma_f32_32x32x16_bf16 v[16:31], v[242:245], v[186:189], v[16:31]
	v_mfma_f32_32x32x16_bf16 v[0:15], v[242:245], v[202:205], v[0:15]
	v_mfma_f32_32x32x16_bf16 v[112:127], v[218:221], v[186:189], v[112:127]
	v_mfma_f32_32x32x16_bf16 v[96:111], v[218:221], v[202:205], v[96:111]
	global_load_dwordx4 v[186:189], v[148:149], off offset:1152
	global_load_dwordx4 v[202:205], v[150:151], off offset:1152
	s_waitcnt vmcnt(9)
	ds_write_b128 v128, v[194:197]
	s_waitcnt vmcnt(8)
	ds_write_b128 v128, v[210:213] offset:9216
	ds_read_b128 v[194:197], v169 offset:64
	ds_read_b128 v[210:213], v169 offset:4672
	ds_read_b128 v[218:221], v155 offset:64
	ds_read_b128 v[226:229], v155 offset:4672
	ds_read_b128 v[234:237], v155 offset:9280
	ds_read_b128 v[242:245], v155 offset:13888
	v_mfma_f32_32x32x16_bf16 v[80:95], v[230:233], v[190:193], v[80:95]
	v_mfma_f32_32x32x16_bf16 v[64:79], v[230:233], v[206:209], v[64:79]
	v_mfma_f32_32x32x16_bf16 v[48:63], v[238:241], v[190:193], v[48:63]
	v_mfma_f32_32x32x16_bf16 v[32:47], v[238:241], v[206:209], v[32:47]
	s_waitcnt lgkmcnt(8)
	v_mfma_f32_32x32x16_bf16 v[16:31], v[246:249], v[190:193], v[16:31]
	v_mfma_f32_32x32x16_bf16 v[0:15], v[246:249], v[206:209], v[0:15]
	v_mfma_f32_32x32x16_bf16 v[112:127], v[222:225], v[190:193], v[112:127]
	v_mfma_f32_32x32x16_bf16 v[96:111], v[222:225], v[206:209], v[96:111]
	global_load_dwordx4 v[190:193], v[144:145], off offset:1152
	global_load_dwordx4 v[206:209], v[146:147], off offset:1152
	s_waitcnt vmcnt(9)
	ds_write_b128 v128, v[198:201] offset:18432
	s_waitcnt vmcnt(8)
	ds_write_b128 v128, v[214:217] offset:27648
	ds_read_b128 v[198:201], v169 offset:96
	ds_read_b128 v[214:217], v169 offset:4704
	ds_read_b128 v[222:225], v155 offset:96
	ds_read_b128 v[230:233], v155 offset:4704
	ds_read_b128 v[238:241], v155 offset:9312
	ds_read_b128 v[246:249], v155 offset:13920
	s_waitcnt lgkmcnt(10)
	v_mfma_f32_32x32x16_bf16 v[80:95], v[226:229], v[194:197], v[80:95]
	v_mfma_f32_32x32x16_bf16 v[64:79], v[226:229], v[210:213], v[64:79]
	s_waitcnt lgkmcnt(9)
	v_mfma_f32_32x32x16_bf16 v[48:63], v[234:237], v[194:197], v[48:63]
	v_mfma_f32_32x32x16_bf16 v[32:47], v[234:237], v[210:213], v[32:47]
	s_waitcnt lgkmcnt(8)
	v_mfma_f32_32x32x16_bf16 v[16:31], v[242:245], v[194:197], v[16:31]
	v_mfma_f32_32x32x16_bf16 v[0:15], v[242:245], v[210:213], v[0:15]
	v_mfma_f32_32x32x16_bf16 v[112:127], v[218:221], v[194:197], v[112:127]
	v_mfma_f32_32x32x16_bf16 v[96:111], v[218:221], v[210:213], v[96:111]
	s_waitcnt vmcnt(7)
	ds_write_b128 v128, v[130:133] offset:36864
	global_load_dwordx4 v[130:133], v[140:141], off offset:1152
	s_waitcnt vmcnt(7)
	ds_write_b128 v128, v[158:161] offset:46080
	global_load_dwordx4 v[158:161], v[138:139], off offset:1152
	s_waitcnt lgkmcnt(4)
	v_mfma_f32_32x32x16_bf16 v[80:95], v[230:233], v[198:201], v[80:95]
	v_mfma_f32_32x32x16_bf16 v[64:79], v[230:233], v[214:217], v[64:79]
	s_waitcnt lgkmcnt(3)
	v_mfma_f32_32x32x16_bf16 v[48:63], v[238:241], v[198:201], v[48:63]
	v_mfma_f32_32x32x16_bf16 v[32:47], v[238:241], v[214:217], v[32:47]
	s_waitcnt lgkmcnt(2)
	v_mfma_f32_32x32x16_bf16 v[16:31], v[246:249], v[198:201], v[16:31]
	v_mfma_f32_32x32x16_bf16 v[0:15], v[246:249], v[214:217], v[0:15]
	v_mfma_f32_32x32x16_bf16 v[112:127], v[222:225], v[198:201], v[112:127]
	v_mfma_f32_32x32x16_bf16 v[96:111], v[222:225], v[214:217], v[96:111]
	global_load_dwordx4 v[194:197], v[134:135], off offset:1152
	global_load_dwordx4 v[198:201], v[136:137], off offset:1152
	s_waitcnt vmcnt(9)
	ds_write_b128 v128, v[172:175] offset:55296
	s_waitcnt vmcnt(8)
	ds_write_b128 v128, v[182:185] offset:64512
	s_waitcnt lgkmcnt(0)
	s_barrier
	ds_read_b128 v[172:175], v163 offset:36864
	ds_read_b128 v[182:185], v163 offset:36896
	ds_read_b128 v[210:213], v163 offset:41472
	ds_read_b128 v[214:217], v163 offset:41504
	ds_read_b128 v[218:221], v154
	ds_read_b128 v[222:225], v154 offset:32
	ds_read_b128 v[226:229], v154 offset:4608
	ds_read_b128 v[230:233], v154 offset:4640
	ds_read_b128 v[234:237], v154 offset:9216
	ds_read_b128 v[238:241], v154 offset:9248
	ds_read_b128 v[242:245], v154 offset:13824
	ds_read_b128 v[246:249], v154 offset:13856
	s_waitcnt lgkmcnt(5)
	v_mfma_f32_32x32x16_bf16 v[80:95], v[226:229], v[172:175], v[80:95]
	v_mfma_f32_32x32x16_bf16 v[64:79], v[226:229], v[210:213], v[64:79]
	s_waitcnt lgkmcnt(3)
	v_mfma_f32_32x32x16_bf16 v[48:63], v[234:237], v[172:175], v[48:63]
	v_mfma_f32_32x32x16_bf16 v[32:47], v[234:237], v[210:213], v[32:47]
	s_waitcnt lgkmcnt(1)
	v_mfma_f32_32x32x16_bf16 v[16:31], v[242:245], v[172:175], v[16:31]
	v_mfma_f32_32x32x16_bf16 v[0:15], v[242:245], v[210:213], v[0:15]
	v_mfma_f32_32x32x16_bf16 v[112:127], v[218:221], v[172:175], v[112:127]
	v_mfma_f32_32x32x16_bf16 v[96:111], v[218:221], v[210:213], v[96:111]
	global_load_dwordx4 v[172:175], v[148:149], off offset:1280
	global_load_dwordx4 v[210:213], v[150:151], off offset:1280
	s_waitcnt vmcnt(9)
	ds_write_b128 v164, v[186:189]
	s_waitcnt vmcnt(8)
	ds_write_b128 v164, v[202:205] offset:9216
	ds_read_b128 v[186:189], v163 offset:36928
	ds_read_b128 v[202:205], v163 offset:41536
	ds_read_b128 v[218:221], v154 offset:64
	ds_read_b128 v[226:229], v154 offset:4672
	ds_read_b128 v[234:237], v154 offset:9280
	ds_read_b128 v[242:245], v154 offset:13888
	v_mfma_f32_32x32x16_bf16 v[80:95], v[230:233], v[182:185], v[80:95]
	v_mfma_f32_32x32x16_bf16 v[64:79], v[230:233], v[214:217], v[64:79]
	v_mfma_f32_32x32x16_bf16 v[48:63], v[238:241], v[182:185], v[48:63]
	v_mfma_f32_32x32x16_bf16 v[32:47], v[238:241], v[214:217], v[32:47]
	s_waitcnt lgkmcnt(8)
	v_mfma_f32_32x32x16_bf16 v[16:31], v[246:249], v[182:185], v[16:31]
	v_mfma_f32_32x32x16_bf16 v[0:15], v[246:249], v[214:217], v[0:15]
	v_mfma_f32_32x32x16_bf16 v[112:127], v[222:225], v[182:185], v[112:127]
	v_mfma_f32_32x32x16_bf16 v[96:111], v[222:225], v[214:217], v[96:111]
	global_load_dwordx4 v[182:185], v[144:145], off offset:1280
	global_load_dwordx4 v[214:217], v[146:147], off offset:1280
	s_waitcnt vmcnt(9)
	ds_write_b128 v164, v[190:193] offset:18432
	s_waitcnt vmcnt(8)
	ds_write_b128 v164, v[206:209] offset:27648
	ds_read_b128 v[190:193], v163 offset:36960
	ds_read_b128 v[206:209], v163 offset:41568
	ds_read_b128 v[222:225], v154 offset:96
	ds_read_b128 v[230:233], v154 offset:4704
	ds_read_b128 v[238:241], v154 offset:9312
	ds_read_b128 v[246:249], v154 offset:13920
	s_waitcnt lgkmcnt(10)
	v_mfma_f32_32x32x16_bf16 v[80:95], v[226:229], v[186:189], v[80:95]
	v_mfma_f32_32x32x16_bf16 v[64:79], v[226:229], v[202:205], v[64:79]
	s_waitcnt lgkmcnt(9)
	v_mfma_f32_32x32x16_bf16 v[48:63], v[234:237], v[186:189], v[48:63]
	v_mfma_f32_32x32x16_bf16 v[32:47], v[234:237], v[202:205], v[32:47]
	s_waitcnt lgkmcnt(8)
	v_mfma_f32_32x32x16_bf16 v[16:31], v[242:245], v[186:189], v[16:31]
	v_mfma_f32_32x32x16_bf16 v[0:15], v[242:245], v[202:205], v[0:15]
	v_mfma_f32_32x32x16_bf16 v[112:127], v[218:221], v[186:189], v[112:127]
	v_mfma_f32_32x32x16_bf16 v[96:111], v[218:221], v[202:205], v[96:111]
	s_waitcnt vmcnt(7)
	ds_write_b128 v165, v[130:133]
	global_load_dwordx4 v[130:133], v[140:141], off offset:1280
	s_waitcnt vmcnt(7)
	ds_write_b128 v166, v[158:161]
	global_load_dwordx4 v[158:161], v[138:139], off offset:1280
	s_waitcnt lgkmcnt(4)
	v_mfma_f32_32x32x16_bf16 v[80:95], v[230:233], v[190:193], v[80:95]
	v_mfma_f32_32x32x16_bf16 v[64:79], v[230:233], v[206:209], v[64:79]
	s_waitcnt lgkmcnt(3)
	v_mfma_f32_32x32x16_bf16 v[48:63], v[238:241], v[190:193], v[48:63]
	v_mfma_f32_32x32x16_bf16 v[32:47], v[238:241], v[206:209], v[32:47]
	s_waitcnt lgkmcnt(2)
	v_mfma_f32_32x32x16_bf16 v[16:31], v[246:249], v[190:193], v[16:31]
	v_mfma_f32_32x32x16_bf16 v[0:15], v[246:249], v[206:209], v[0:15]
	v_mfma_f32_32x32x16_bf16 v[112:127], v[222:225], v[190:193], v[112:127]
	v_mfma_f32_32x32x16_bf16 v[96:111], v[222:225], v[206:209], v[96:111]
	global_load_dwordx4 v[186:189], v[134:135], off offset:1280
	global_load_dwordx4 v[190:193], v[136:137], off offset:1280
	s_waitcnt vmcnt(9)
	ds_write_b128 v167, v[194:197]
	s_waitcnt vmcnt(8)
	ds_write_b128 v168, v[198:201]
	s_waitcnt lgkmcnt(0)
	s_barrier
	ds_read_b128 v[194:197], v169
	ds_read_b128 v[198:201], v169 offset:32
	ds_read_b128 v[202:205], v169 offset:4608
	ds_read_b128 v[206:209], v169 offset:4640
	ds_read_b128 v[218:221], v155
	ds_read_b128 v[222:225], v155 offset:32
	ds_read_b128 v[226:229], v155 offset:4608
	ds_read_b128 v[230:233], v155 offset:4640
	ds_read_b128 v[234:237], v155 offset:9216
	ds_read_b128 v[238:241], v155 offset:9248
	ds_read_b128 v[242:245], v155 offset:13824
	ds_read_b128 v[246:249], v155 offset:13856
	s_waitcnt lgkmcnt(5)
	v_mfma_f32_32x32x16_bf16 v[80:95], v[226:229], v[194:197], v[80:95]
	v_mfma_f32_32x32x16_bf16 v[64:79], v[226:229], v[202:205], v[64:79]
	s_waitcnt lgkmcnt(3)
	v_mfma_f32_32x32x16_bf16 v[48:63], v[234:237], v[194:197], v[48:63]
	v_mfma_f32_32x32x16_bf16 v[32:47], v[234:237], v[202:205], v[32:47]
	s_waitcnt lgkmcnt(1)
	v_mfma_f32_32x32x16_bf16 v[16:31], v[242:245], v[194:197], v[16:31]
	v_mfma_f32_32x32x16_bf16 v[0:15], v[242:245], v[202:205], v[0:15]
	v_mfma_f32_32x32x16_bf16 v[112:127], v[218:221], v[194:197], v[112:127]
	v_mfma_f32_32x32x16_bf16 v[96:111], v[218:221], v[202:205], v[96:111]
	global_load_dwordx4 v[194:197], v[148:149], off offset:1408
	global_load_dwordx4 v[202:205], v[150:151], off offset:1408
	s_waitcnt vmcnt(9)
	ds_write_b128 v128, v[172:175]
	s_waitcnt vmcnt(8)
	ds_write_b128 v128, v[210:213] offset:9216
	ds_read_b128 v[172:175], v169 offset:64
	ds_read_b128 v[210:213], v169 offset:4672
	ds_read_b128 v[218:221], v155 offset:64
	ds_read_b128 v[226:229], v155 offset:4672
	ds_read_b128 v[234:237], v155 offset:9280
	ds_read_b128 v[242:245], v155 offset:13888
	v_mfma_f32_32x32x16_bf16 v[80:95], v[230:233], v[198:201], v[80:95]
	v_mfma_f32_32x32x16_bf16 v[64:79], v[230:233], v[206:209], v[64:79]
	v_mfma_f32_32x32x16_bf16 v[48:63], v[238:241], v[198:201], v[48:63]
	v_mfma_f32_32x32x16_bf16 v[32:47], v[238:241], v[206:209], v[32:47]
	s_waitcnt lgkmcnt(8)
	v_mfma_f32_32x32x16_bf16 v[16:31], v[246:249], v[198:201], v[16:31]
	v_mfma_f32_32x32x16_bf16 v[0:15], v[246:249], v[206:209], v[0:15]
	v_mfma_f32_32x32x16_bf16 v[112:127], v[222:225], v[198:201], v[112:127]
	v_mfma_f32_32x32x16_bf16 v[96:111], v[222:225], v[206:209], v[96:111]
	global_load_dwordx4 v[198:201], v[144:145], off offset:1408
	global_load_dwordx4 v[206:209], v[146:147], off offset:1408
	s_waitcnt vmcnt(9)
	ds_write_b128 v128, v[182:185] offset:18432
	s_waitcnt vmcnt(8)
	ds_write_b128 v128, v[214:217] offset:27648
	ds_read_b128 v[182:185], v169 offset:96
	ds_read_b128 v[214:217], v169 offset:4704
	ds_read_b128 v[222:225], v155 offset:96
	ds_read_b128 v[230:233], v155 offset:4704
	ds_read_b128 v[238:241], v155 offset:9312
	ds_read_b128 v[246:249], v155 offset:13920
	s_waitcnt lgkmcnt(10)
	v_mfma_f32_32x32x16_bf16 v[80:95], v[226:229], v[172:175], v[80:95]
	v_mfma_f32_32x32x16_bf16 v[64:79], v[226:229], v[210:213], v[64:79]
	s_waitcnt lgkmcnt(9)
	v_mfma_f32_32x32x16_bf16 v[48:63], v[234:237], v[172:175], v[48:63]
	v_mfma_f32_32x32x16_bf16 v[32:47], v[234:237], v[210:213], v[32:47]
	s_waitcnt lgkmcnt(8)
	v_mfma_f32_32x32x16_bf16 v[16:31], v[242:245], v[172:175], v[16:31]
	v_mfma_f32_32x32x16_bf16 v[0:15], v[242:245], v[210:213], v[0:15]
	v_mfma_f32_32x32x16_bf16 v[112:127], v[218:221], v[172:175], v[112:127]
	v_mfma_f32_32x32x16_bf16 v[96:111], v[218:221], v[210:213], v[96:111]
	s_waitcnt vmcnt(7)
	ds_write_b128 v128, v[130:133] offset:36864
	global_load_dwordx4 v[130:133], v[140:141], off offset:1408
	s_waitcnt vmcnt(7)
	ds_write_b128 v128, v[158:161] offset:46080
	global_load_dwordx4 v[158:161], v[138:139], off offset:1408
	s_waitcnt lgkmcnt(4)
	v_mfma_f32_32x32x16_bf16 v[80:95], v[230:233], v[182:185], v[80:95]
	v_mfma_f32_32x32x16_bf16 v[64:79], v[230:233], v[214:217], v[64:79]
	s_waitcnt lgkmcnt(3)
	v_mfma_f32_32x32x16_bf16 v[48:63], v[238:241], v[182:185], v[48:63]
	v_mfma_f32_32x32x16_bf16 v[32:47], v[238:241], v[214:217], v[32:47]
	s_waitcnt lgkmcnt(2)
	v_mfma_f32_32x32x16_bf16 v[16:31], v[246:249], v[182:185], v[16:31]
	v_mfma_f32_32x32x16_bf16 v[0:15], v[246:249], v[214:217], v[0:15]
	v_mfma_f32_32x32x16_bf16 v[112:127], v[222:225], v[182:185], v[112:127]
	v_mfma_f32_32x32x16_bf16 v[96:111], v[222:225], v[214:217], v[96:111]
	global_load_dwordx4 v[172:175], v[134:135], off offset:1408
	global_load_dwordx4 v[182:185], v[136:137], off offset:1408
	s_waitcnt vmcnt(9)
	ds_write_b128 v128, v[186:189] offset:55296
	s_waitcnt vmcnt(8)
	ds_write_b128 v128, v[190:193] offset:64512
	s_waitcnt lgkmcnt(0)
	s_barrier
	ds_read_b128 v[186:189], v163 offset:36864
	ds_read_b128 v[190:193], v163 offset:36896
	ds_read_b128 v[210:213], v163 offset:41472
	ds_read_b128 v[214:217], v163 offset:41504
	ds_read_b128 v[218:221], v154
	ds_read_b128 v[222:225], v154 offset:32
	ds_read_b128 v[226:229], v154 offset:4608
	ds_read_b128 v[230:233], v154 offset:4640
	ds_read_b128 v[234:237], v154 offset:9216
	ds_read_b128 v[238:241], v154 offset:9248
	ds_read_b128 v[242:245], v154 offset:13824
	ds_read_b128 v[246:249], v154 offset:13856
	s_waitcnt lgkmcnt(5)
	v_mfma_f32_32x32x16_bf16 v[80:95], v[226:229], v[186:189], v[80:95]
	v_mfma_f32_32x32x16_bf16 v[64:79], v[226:229], v[210:213], v[64:79]
	s_waitcnt lgkmcnt(3)
	v_mfma_f32_32x32x16_bf16 v[48:63], v[234:237], v[186:189], v[48:63]
	v_mfma_f32_32x32x16_bf16 v[32:47], v[234:237], v[210:213], v[32:47]
	s_waitcnt lgkmcnt(1)
	v_mfma_f32_32x32x16_bf16 v[16:31], v[242:245], v[186:189], v[16:31]
	v_mfma_f32_32x32x16_bf16 v[0:15], v[242:245], v[210:213], v[0:15]
	v_mfma_f32_32x32x16_bf16 v[112:127], v[218:221], v[186:189], v[112:127]
	v_mfma_f32_32x32x16_bf16 v[96:111], v[218:221], v[210:213], v[96:111]
	global_load_dwordx4 v[186:189], v[148:149], off offset:1536
	global_load_dwordx4 v[210:213], v[150:151], off offset:1536
	s_waitcnt vmcnt(9)
	ds_write_b128 v164, v[194:197]
	s_waitcnt vmcnt(8)
	ds_write_b128 v164, v[202:205] offset:9216
	ds_read_b128 v[194:197], v163 offset:36928
	ds_read_b128 v[202:205], v163 offset:41536
	ds_read_b128 v[218:221], v154 offset:64
	ds_read_b128 v[226:229], v154 offset:4672
	ds_read_b128 v[234:237], v154 offset:9280
	ds_read_b128 v[242:245], v154 offset:13888
	v_mfma_f32_32x32x16_bf16 v[80:95], v[230:233], v[190:193], v[80:95]
	v_mfma_f32_32x32x16_bf16 v[64:79], v[230:233], v[214:217], v[64:79]
	v_mfma_f32_32x32x16_bf16 v[48:63], v[238:241], v[190:193], v[48:63]
	v_mfma_f32_32x32x16_bf16 v[32:47], v[238:241], v[214:217], v[32:47]
	s_waitcnt lgkmcnt(8)
	v_mfma_f32_32x32x16_bf16 v[16:31], v[246:249], v[190:193], v[16:31]
	v_mfma_f32_32x32x16_bf16 v[0:15], v[246:249], v[214:217], v[0:15]
	v_mfma_f32_32x32x16_bf16 v[112:127], v[222:225], v[190:193], v[112:127]
	v_mfma_f32_32x32x16_bf16 v[96:111], v[222:225], v[214:217], v[96:111]
	global_load_dwordx4 v[190:193], v[144:145], off offset:1536
	global_load_dwordx4 v[214:217], v[146:147], off offset:1536
	s_waitcnt vmcnt(9)
	ds_write_b128 v164, v[198:201] offset:18432
	s_waitcnt vmcnt(8)
	ds_write_b128 v164, v[206:209] offset:27648
	ds_read_b128 v[198:201], v163 offset:36960
	ds_read_b128 v[206:209], v163 offset:41568
	ds_read_b128 v[222:225], v154 offset:96
	ds_read_b128 v[230:233], v154 offset:4704
	ds_read_b128 v[238:241], v154 offset:9312
	ds_read_b128 v[246:249], v154 offset:13920
	s_waitcnt lgkmcnt(10)
	v_mfma_f32_32x32x16_bf16 v[80:95], v[226:229], v[194:197], v[80:95]
	v_mfma_f32_32x32x16_bf16 v[64:79], v[226:229], v[202:205], v[64:79]
	s_waitcnt lgkmcnt(9)
	v_mfma_f32_32x32x16_bf16 v[48:63], v[234:237], v[194:197], v[48:63]
	v_mfma_f32_32x32x16_bf16 v[32:47], v[234:237], v[202:205], v[32:47]
	s_waitcnt lgkmcnt(8)
	v_mfma_f32_32x32x16_bf16 v[16:31], v[242:245], v[194:197], v[16:31]
	v_mfma_f32_32x32x16_bf16 v[0:15], v[242:245], v[202:205], v[0:15]
	v_mfma_f32_32x32x16_bf16 v[112:127], v[218:221], v[194:197], v[112:127]
	v_mfma_f32_32x32x16_bf16 v[96:111], v[218:221], v[202:205], v[96:111]
	s_waitcnt vmcnt(7)
	ds_write_b128 v165, v[130:133]
	global_load_dwordx4 v[130:133], v[140:141], off offset:1536
	s_waitcnt vmcnt(7)
	ds_write_b128 v166, v[158:161]
	global_load_dwordx4 v[158:161], v[138:139], off offset:1536
	s_waitcnt lgkmcnt(4)
	v_mfma_f32_32x32x16_bf16 v[80:95], v[230:233], v[198:201], v[80:95]
	v_mfma_f32_32x32x16_bf16 v[64:79], v[230:233], v[206:209], v[64:79]
	s_waitcnt lgkmcnt(3)
	v_mfma_f32_32x32x16_bf16 v[48:63], v[238:241], v[198:201], v[48:63]
	v_mfma_f32_32x32x16_bf16 v[32:47], v[238:241], v[206:209], v[32:47]
	s_waitcnt lgkmcnt(2)
	v_mfma_f32_32x32x16_bf16 v[16:31], v[246:249], v[198:201], v[16:31]
	v_mfma_f32_32x32x16_bf16 v[0:15], v[246:249], v[206:209], v[0:15]
	v_mfma_f32_32x32x16_bf16 v[112:127], v[222:225], v[198:201], v[112:127]
	v_mfma_f32_32x32x16_bf16 v[96:111], v[222:225], v[206:209], v[96:111]
	global_load_dwordx4 v[194:197], v[134:135], off offset:1536
	global_load_dwordx4 v[198:201], v[136:137], off offset:1536
	s_waitcnt vmcnt(9)
	ds_write_b128 v167, v[172:175]
	s_waitcnt vmcnt(8)
	ds_write_b128 v168, v[182:185]
	s_waitcnt lgkmcnt(0)
	s_barrier
	ds_read_b128 v[172:175], v169
	ds_read_b128 v[182:185], v169 offset:32
	ds_read_b128 v[202:205], v169 offset:4608
	ds_read_b128 v[206:209], v169 offset:4640
	ds_read_b128 v[218:221], v155
	ds_read_b128 v[222:225], v155 offset:32
	ds_read_b128 v[226:229], v155 offset:4608
	ds_read_b128 v[230:233], v155 offset:4640
	ds_read_b128 v[234:237], v155 offset:9216
	ds_read_b128 v[238:241], v155 offset:9248
	ds_read_b128 v[242:245], v155 offset:13824
	ds_read_b128 v[246:249], v155 offset:13856
	s_waitcnt lgkmcnt(5)
	v_mfma_f32_32x32x16_bf16 v[80:95], v[226:229], v[172:175], v[80:95]
	v_mfma_f32_32x32x16_bf16 v[64:79], v[226:229], v[202:205], v[64:79]
	s_waitcnt lgkmcnt(3)
	v_mfma_f32_32x32x16_bf16 v[48:63], v[234:237], v[172:175], v[48:63]
	v_mfma_f32_32x32x16_bf16 v[32:47], v[234:237], v[202:205], v[32:47]
	s_waitcnt lgkmcnt(1)
	v_mfma_f32_32x32x16_bf16 v[16:31], v[242:245], v[172:175], v[16:31]
	v_mfma_f32_32x32x16_bf16 v[0:15], v[242:245], v[202:205], v[0:15]
	v_mfma_f32_32x32x16_bf16 v[112:127], v[218:221], v[172:175], v[112:127]
	v_mfma_f32_32x32x16_bf16 v[96:111], v[218:221], v[202:205], v[96:111]
	global_load_dwordx4 v[172:175], v[148:149], off offset:1664
	global_load_dwordx4 v[202:205], v[150:151], off offset:1664
	s_waitcnt vmcnt(9)
	ds_write_b128 v128, v[186:189]
	s_waitcnt vmcnt(8)
	ds_write_b128 v128, v[210:213] offset:9216
	ds_read_b128 v[186:189], v169 offset:64
	ds_read_b128 v[210:213], v169 offset:4672
	ds_read_b128 v[218:221], v155 offset:64
	ds_read_b128 v[226:229], v155 offset:4672
	ds_read_b128 v[234:237], v155 offset:9280
	ds_read_b128 v[242:245], v155 offset:13888
	v_mfma_f32_32x32x16_bf16 v[80:95], v[230:233], v[182:185], v[80:95]
	v_mfma_f32_32x32x16_bf16 v[64:79], v[230:233], v[206:209], v[64:79]
	v_mfma_f32_32x32x16_bf16 v[48:63], v[238:241], v[182:185], v[48:63]
	v_mfma_f32_32x32x16_bf16 v[32:47], v[238:241], v[206:209], v[32:47]
	s_waitcnt lgkmcnt(8)
	v_mfma_f32_32x32x16_bf16 v[16:31], v[246:249], v[182:185], v[16:31]
	v_mfma_f32_32x32x16_bf16 v[0:15], v[246:249], v[206:209], v[0:15]
	v_mfma_f32_32x32x16_bf16 v[112:127], v[222:225], v[182:185], v[112:127]
	v_mfma_f32_32x32x16_bf16 v[96:111], v[222:225], v[206:209], v[96:111]
	global_load_dwordx4 v[182:185], v[144:145], off offset:1664
	global_load_dwordx4 v[206:209], v[146:147], off offset:1664
	s_waitcnt vmcnt(9)
	ds_write_b128 v128, v[190:193] offset:18432
	s_waitcnt vmcnt(8)
	ds_write_b128 v128, v[214:217] offset:27648
	ds_read_b128 v[190:193], v169 offset:96
	ds_read_b128 v[214:217], v169 offset:4704
	ds_read_b128 v[222:225], v155 offset:96
	ds_read_b128 v[230:233], v155 offset:4704
	ds_read_b128 v[238:241], v155 offset:9312
	ds_read_b128 v[246:249], v155 offset:13920
	s_waitcnt lgkmcnt(10)
	v_mfma_f32_32x32x16_bf16 v[80:95], v[226:229], v[186:189], v[80:95]
	v_mfma_f32_32x32x16_bf16 v[64:79], v[226:229], v[210:213], v[64:79]
	s_waitcnt lgkmcnt(9)
	v_mfma_f32_32x32x16_bf16 v[48:63], v[234:237], v[186:189], v[48:63]
	v_mfma_f32_32x32x16_bf16 v[32:47], v[234:237], v[210:213], v[32:47]
	s_waitcnt lgkmcnt(8)
	v_mfma_f32_32x32x16_bf16 v[16:31], v[242:245], v[186:189], v[16:31]
	v_mfma_f32_32x32x16_bf16 v[0:15], v[242:245], v[210:213], v[0:15]
	v_mfma_f32_32x32x16_bf16 v[112:127], v[218:221], v[186:189], v[112:127]
	v_mfma_f32_32x32x16_bf16 v[96:111], v[218:221], v[210:213], v[96:111]
	s_waitcnt vmcnt(7)
	ds_write_b128 v128, v[130:133] offset:36864
	global_load_dwordx4 v[130:133], v[140:141], off offset:1664
	s_waitcnt vmcnt(7)
	ds_write_b128 v128, v[158:161] offset:46080
	global_load_dwordx4 v[158:161], v[138:139], off offset:1664
	s_waitcnt lgkmcnt(4)
	v_mfma_f32_32x32x16_bf16 v[80:95], v[230:233], v[190:193], v[80:95]
	v_mfma_f32_32x32x16_bf16 v[64:79], v[230:233], v[214:217], v[64:79]
	s_waitcnt lgkmcnt(3)
	v_mfma_f32_32x32x16_bf16 v[48:63], v[238:241], v[190:193], v[48:63]
	v_mfma_f32_32x32x16_bf16 v[32:47], v[238:241], v[214:217], v[32:47]
	s_waitcnt lgkmcnt(2)
	v_mfma_f32_32x32x16_bf16 v[16:31], v[246:249], v[190:193], v[16:31]
	v_mfma_f32_32x32x16_bf16 v[0:15], v[246:249], v[214:217], v[0:15]
	v_mfma_f32_32x32x16_bf16 v[112:127], v[222:225], v[190:193], v[112:127]
	v_mfma_f32_32x32x16_bf16 v[96:111], v[222:225], v[214:217], v[96:111]
	global_load_dwordx4 v[186:189], v[134:135], off offset:1664
	global_load_dwordx4 v[190:193], v[136:137], off offset:1664
	s_waitcnt vmcnt(9)
	ds_write_b128 v128, v[194:197] offset:55296
	s_waitcnt vmcnt(8)
	ds_write_b128 v128, v[198:201] offset:64512
	s_waitcnt lgkmcnt(0)
	s_barrier
	ds_read_b128 v[194:197], v163 offset:36864
	ds_read_b128 v[198:201], v163 offset:36896
	ds_read_b128 v[210:213], v163 offset:41472
	ds_read_b128 v[214:217], v163 offset:41504
	ds_read_b128 v[218:221], v154
	ds_read_b128 v[222:225], v154 offset:32
	ds_read_b128 v[226:229], v154 offset:4608
	ds_read_b128 v[230:233], v154 offset:4640
	ds_read_b128 v[234:237], v154 offset:9216
	ds_read_b128 v[238:241], v154 offset:9248
	ds_read_b128 v[242:245], v154 offset:13824
	ds_read_b128 v[246:249], v154 offset:13856
	s_waitcnt lgkmcnt(5)
	v_mfma_f32_32x32x16_bf16 v[80:95], v[226:229], v[194:197], v[80:95]
	v_mfma_f32_32x32x16_bf16 v[64:79], v[226:229], v[210:213], v[64:79]
	s_waitcnt lgkmcnt(3)
	v_mfma_f32_32x32x16_bf16 v[48:63], v[234:237], v[194:197], v[48:63]
	v_mfma_f32_32x32x16_bf16 v[32:47], v[234:237], v[210:213], v[32:47]
	s_waitcnt lgkmcnt(1)
	v_mfma_f32_32x32x16_bf16 v[16:31], v[242:245], v[194:197], v[16:31]
	v_mfma_f32_32x32x16_bf16 v[0:15], v[242:245], v[210:213], v[0:15]
	v_mfma_f32_32x32x16_bf16 v[112:127], v[218:221], v[194:197], v[112:127]
	v_mfma_f32_32x32x16_bf16 v[96:111], v[218:221], v[210:213], v[96:111]
	global_load_dwordx4 v[194:197], v[148:149], off offset:1792
	global_load_dwordx4 v[210:213], v[150:151], off offset:1792
	s_waitcnt vmcnt(9)
	ds_write_b128 v164, v[172:175]
	s_waitcnt vmcnt(8)
	ds_write_b128 v164, v[202:205] offset:9216
	ds_read_b128 v[172:175], v163 offset:36928
	ds_read_b128 v[202:205], v163 offset:41536
	ds_read_b128 v[218:221], v154 offset:64
	ds_read_b128 v[226:229], v154 offset:4672
	ds_read_b128 v[234:237], v154 offset:9280
	ds_read_b128 v[242:245], v154 offset:13888
	v_mfma_f32_32x32x16_bf16 v[80:95], v[230:233], v[198:201], v[80:95]
	v_mfma_f32_32x32x16_bf16 v[64:79], v[230:233], v[214:217], v[64:79]
	v_mfma_f32_32x32x16_bf16 v[48:63], v[238:241], v[198:201], v[48:63]
	v_mfma_f32_32x32x16_bf16 v[32:47], v[238:241], v[214:217], v[32:47]
	s_waitcnt lgkmcnt(8)
	v_mfma_f32_32x32x16_bf16 v[16:31], v[246:249], v[198:201], v[16:31]
	v_mfma_f32_32x32x16_bf16 v[0:15], v[246:249], v[214:217], v[0:15]
	v_mfma_f32_32x32x16_bf16 v[112:127], v[222:225], v[198:201], v[112:127]
	v_mfma_f32_32x32x16_bf16 v[96:111], v[222:225], v[214:217], v[96:111]
	global_load_dwordx4 v[198:201], v[144:145], off offset:1792
	global_load_dwordx4 v[214:217], v[146:147], off offset:1792
	s_waitcnt vmcnt(9)
	ds_write_b128 v164, v[182:185] offset:18432
	s_waitcnt vmcnt(8)
	ds_write_b128 v164, v[206:209] offset:27648
	ds_read_b128 v[182:185], v163 offset:36960
	ds_read_b128 v[206:209], v163 offset:41568
	ds_read_b128 v[222:225], v154 offset:96
	ds_read_b128 v[230:233], v154 offset:4704
	ds_read_b128 v[238:241], v154 offset:9312
	ds_read_b128 v[246:249], v154 offset:13920
	s_waitcnt lgkmcnt(10)
	v_mfma_f32_32x32x16_bf16 v[80:95], v[226:229], v[172:175], v[80:95]
	v_mfma_f32_32x32x16_bf16 v[64:79], v[226:229], v[202:205], v[64:79]
	s_waitcnt lgkmcnt(9)
	v_mfma_f32_32x32x16_bf16 v[48:63], v[234:237], v[172:175], v[48:63]
	v_mfma_f32_32x32x16_bf16 v[32:47], v[234:237], v[202:205], v[32:47]
	s_waitcnt lgkmcnt(8)
	v_mfma_f32_32x32x16_bf16 v[16:31], v[242:245], v[172:175], v[16:31]
	v_mfma_f32_32x32x16_bf16 v[0:15], v[242:245], v[202:205], v[0:15]
	v_mfma_f32_32x32x16_bf16 v[112:127], v[218:221], v[172:175], v[112:127]
	v_mfma_f32_32x32x16_bf16 v[96:111], v[218:221], v[202:205], v[96:111]
	s_waitcnt vmcnt(7)
	ds_write_b128 v165, v[130:133]
	global_load_dwordx4 v[130:133], v[140:141], off offset:1792
	s_waitcnt vmcnt(7)
	ds_write_b128 v166, v[158:161]
	global_load_dwordx4 v[158:161], v[138:139], off offset:1792
	s_waitcnt lgkmcnt(4)
	v_mfma_f32_32x32x16_bf16 v[80:95], v[230:233], v[182:185], v[80:95]
	v_mfma_f32_32x32x16_bf16 v[64:79], v[230:233], v[206:209], v[64:79]
	s_waitcnt lgkmcnt(3)
	v_mfma_f32_32x32x16_bf16 v[48:63], v[238:241], v[182:185], v[48:63]
	v_mfma_f32_32x32x16_bf16 v[32:47], v[238:241], v[206:209], v[32:47]
	s_waitcnt lgkmcnt(2)
	v_mfma_f32_32x32x16_bf16 v[16:31], v[246:249], v[182:185], v[16:31]
	v_mfma_f32_32x32x16_bf16 v[0:15], v[246:249], v[206:209], v[0:15]
	v_mfma_f32_32x32x16_bf16 v[112:127], v[222:225], v[182:185], v[112:127]
	v_mfma_f32_32x32x16_bf16 v[96:111], v[222:225], v[206:209], v[96:111]
	global_load_dwordx4 v[172:175], v[134:135], off offset:1792
	global_load_dwordx4 v[182:185], v[136:137], off offset:1792
	s_waitcnt vmcnt(9)
	ds_write_b128 v167, v[186:189]
	s_waitcnt vmcnt(8)
	ds_write_b128 v168, v[190:193]
	s_waitcnt lgkmcnt(0)
	s_barrier
	ds_read_b128 v[186:189], v169
	ds_read_b128 v[190:193], v169 offset:32
	ds_read_b128 v[202:205], v169 offset:4608
	ds_read_b128 v[206:209], v169 offset:4640
	ds_read_b128 v[218:221], v155
	ds_read_b128 v[222:225], v155 offset:32
	ds_read_b128 v[226:229], v155 offset:4608
	ds_read_b128 v[230:233], v155 offset:4640
	ds_read_b128 v[234:237], v155 offset:9216
	ds_read_b128 v[238:241], v155 offset:9248
	ds_read_b128 v[242:245], v155 offset:13824
	ds_read_b128 v[246:249], v155 offset:13856
	s_waitcnt lgkmcnt(5)
	v_mfma_f32_32x32x16_bf16 v[80:95], v[226:229], v[186:189], v[80:95]
	v_mfma_f32_32x32x16_bf16 v[64:79], v[226:229], v[202:205], v[64:79]
	s_waitcnt lgkmcnt(3)
	v_mfma_f32_32x32x16_bf16 v[48:63], v[234:237], v[186:189], v[48:63]
	v_mfma_f32_32x32x16_bf16 v[32:47], v[234:237], v[202:205], v[32:47]
	s_waitcnt lgkmcnt(1)
	v_mfma_f32_32x32x16_bf16 v[16:31], v[242:245], v[186:189], v[16:31]
	v_mfma_f32_32x32x16_bf16 v[0:15], v[242:245], v[202:205], v[0:15]
	v_mfma_f32_32x32x16_bf16 v[112:127], v[218:221], v[186:189], v[112:127]
	v_mfma_f32_32x32x16_bf16 v[96:111], v[218:221], v[202:205], v[96:111]
	global_load_dwordx4 v[186:189], v[148:149], off offset:1920
	s_nop 0
	global_load_dwordx4 v[148:151], v[150:151], off offset:1920
	s_waitcnt vmcnt(9)
	ds_write_b128 v128, v[194:197]
	s_waitcnt vmcnt(8)
	ds_write_b128 v128, v[210:213] offset:9216
	ds_read_b128 v[194:197], v169 offset:64
	ds_read_b128 v[202:205], v169 offset:4672
	ds_read_b128 v[210:213], v155 offset:64
	ds_read_b128 v[218:221], v155 offset:4672
	ds_read_b128 v[226:229], v155 offset:9280
	ds_read_b128 v[234:237], v155 offset:13888
	v_mfma_f32_32x32x16_bf16 v[80:95], v[230:233], v[190:193], v[80:95]
	v_mfma_f32_32x32x16_bf16 v[64:79], v[230:233], v[206:209], v[64:79]
	v_mfma_f32_32x32x16_bf16 v[48:63], v[238:241], v[190:193], v[48:63]
	v_mfma_f32_32x32x16_bf16 v[32:47], v[238:241], v[206:209], v[32:47]
	s_waitcnt lgkmcnt(8)
	v_mfma_f32_32x32x16_bf16 v[16:31], v[246:249], v[190:193], v[16:31]
	v_mfma_f32_32x32x16_bf16 v[0:15], v[246:249], v[206:209], v[0:15]
	v_mfma_f32_32x32x16_bf16 v[112:127], v[222:225], v[190:193], v[112:127]
	v_mfma_f32_32x32x16_bf16 v[96:111], v[222:225], v[206:209], v[96:111]
	global_load_dwordx4 v[190:193], v[144:145], off offset:1920
	s_nop 0
	global_load_dwordx4 v[144:147], v[146:147], off offset:1920
	s_waitcnt vmcnt(9)
	ds_write_b128 v128, v[198:201] offset:18432
	s_waitcnt vmcnt(8)
	ds_write_b128 v128, v[214:217] offset:27648
	ds_read_b128 v[198:201], v169 offset:96
	ds_read_b128 v[206:209], v169 offset:4704
	ds_read_b128 v[214:217], v155 offset:96
	ds_read_b128 v[222:225], v155 offset:4704
	ds_read_b128 v[230:233], v155 offset:9312
	ds_read_b128 v[238:241], v155 offset:13920
	s_waitcnt lgkmcnt(10)
	v_mfma_f32_32x32x16_bf16 v[80:95], v[218:221], v[194:197], v[80:95]
	v_mfma_f32_32x32x16_bf16 v[64:79], v[218:221], v[202:205], v[64:79]
	s_waitcnt lgkmcnt(9)
	v_mfma_f32_32x32x16_bf16 v[48:63], v[226:229], v[194:197], v[48:63]
	v_mfma_f32_32x32x16_bf16 v[32:47], v[226:229], v[202:205], v[32:47]
	s_waitcnt lgkmcnt(8)
	v_mfma_f32_32x32x16_bf16 v[16:31], v[234:237], v[194:197], v[16:31]
	v_mfma_f32_32x32x16_bf16 v[0:15], v[234:237], v[202:205], v[0:15]
	v_mfma_f32_32x32x16_bf16 v[112:127], v[210:213], v[194:197], v[112:127]
	v_mfma_f32_32x32x16_bf16 v[96:111], v[210:213], v[202:205], v[96:111]
	s_waitcnt vmcnt(7)
	ds_write_b128 v128, v[130:133] offset:36864
	global_load_dwordx4 v[130:133], v[140:141], off offset:1920
	s_waitcnt vmcnt(7)
	ds_write_b128 v128, v[158:161] offset:46080
	global_load_dwordx4 v[138:141], v[138:139], off offset:1920
	s_waitcnt lgkmcnt(4)
	v_mfma_f32_32x32x16_bf16 v[80:95], v[222:225], v[198:201], v[80:95]
	v_mfma_f32_32x32x16_bf16 v[64:79], v[222:225], v[206:209], v[64:79]
	s_waitcnt lgkmcnt(3)
	v_mfma_f32_32x32x16_bf16 v[48:63], v[230:233], v[198:201], v[48:63]
	v_mfma_f32_32x32x16_bf16 v[32:47], v[230:233], v[206:209], v[32:47]
	s_waitcnt lgkmcnt(2)
	v_mfma_f32_32x32x16_bf16 v[16:31], v[238:241], v[198:201], v[16:31]
	v_mfma_f32_32x32x16_bf16 v[0:15], v[238:241], v[206:209], v[0:15]
	v_mfma_f32_32x32x16_bf16 v[112:127], v[214:217], v[198:201], v[112:127]
	v_mfma_f32_32x32x16_bf16 v[96:111], v[214:217], v[206:209], v[96:111]
	global_load_dwordx4 v[158:161], v[134:135], off offset:1920
	s_nop 0
	global_load_dwordx4 v[134:137], v[136:137], off offset:1920
	s_waitcnt vmcnt(9)
	ds_write_b128 v128, v[172:175] offset:55296
	s_waitcnt vmcnt(8)
	ds_write_b128 v128, v[182:185] offset:64512
	s_waitcnt lgkmcnt(0)
	s_barrier
	ds_read_b128 v[172:175], v163 offset:36864
	ds_read_b128 v[182:185], v163 offset:36896
	ds_read_b128 v[194:197], v163 offset:41472
	ds_read_b128 v[198:201], v163 offset:41504
	ds_read_b128 v[202:205], v154
	ds_read_b128 v[206:209], v154 offset:32
	ds_read_b128 v[210:213], v154 offset:4608
	ds_read_b128 v[214:217], v154 offset:4640
	ds_read_b128 v[218:221], v154 offset:9216
	ds_read_b128 v[222:225], v154 offset:9248
	ds_read_b128 v[226:229], v154 offset:13824
	ds_read_b128 v[230:233], v154 offset:13856
	s_waitcnt lgkmcnt(5)
	v_mfma_f32_32x32x16_bf16 v[80:95], v[210:213], v[172:175], v[80:95]
	v_mfma_f32_32x32x16_bf16 v[64:79], v[210:213], v[194:197], v[64:79]
	s_waitcnt lgkmcnt(3)
	v_mfma_f32_32x32x16_bf16 v[48:63], v[218:221], v[172:175], v[48:63]
	v_mfma_f32_32x32x16_bf16 v[32:47], v[218:221], v[194:197], v[32:47]
	s_waitcnt lgkmcnt(1)
	v_mfma_f32_32x32x16_bf16 v[16:31], v[226:229], v[172:175], v[16:31]
	v_mfma_f32_32x32x16_bf16 v[0:15], v[226:229], v[194:197], v[0:15]
	v_mfma_f32_32x32x16_bf16 v[112:127], v[202:205], v[172:175], v[112:127]
	v_mfma_f32_32x32x16_bf16 v[96:111], v[202:205], v[194:197], v[96:111]
	s_waitcnt vmcnt(7)
	ds_write_b128 v164, v[186:189]
	s_waitcnt vmcnt(6)
	ds_write_b128 v164, v[148:151] offset:9216
	ds_read_b128 v[148:151], v163 offset:36928
	ds_read_b128 v[172:175], v163 offset:41536
	ds_read_b128 v[186:189], v154 offset:64
	ds_read_b128 v[194:197], v154 offset:4672
	ds_read_b128 v[202:205], v154 offset:9280
	ds_read_b128 v[210:213], v154 offset:13888
	v_mfma_f32_32x32x16_bf16 v[80:95], v[214:217], v[182:185], v[80:95]
	v_mfma_f32_32x32x16_bf16 v[64:79], v[214:217], v[198:201], v[64:79]
	v_mfma_f32_32x32x16_bf16 v[48:63], v[222:225], v[182:185], v[48:63]
	v_mfma_f32_32x32x16_bf16 v[32:47], v[222:225], v[198:201], v[32:47]
	s_waitcnt lgkmcnt(8)
	v_mfma_f32_32x32x16_bf16 v[16:31], v[230:233], v[182:185], v[16:31]
	v_mfma_f32_32x32x16_bf16 v[0:15], v[230:233], v[198:201], v[0:15]
	v_mfma_f32_32x32x16_bf16 v[112:127], v[206:209], v[182:185], v[112:127]
	v_mfma_f32_32x32x16_bf16 v[96:111], v[206:209], v[198:201], v[96:111]
	s_waitcnt vmcnt(5)
	ds_write_b128 v164, v[190:193] offset:18432
	s_waitcnt vmcnt(4)
	ds_write_b128 v164, v[144:147] offset:27648
	ds_read_b128 v[144:147], v163 offset:36960
	ds_read_b128 v[182:185], v163 offset:41568
	ds_read_b128 v[190:193], v154 offset:96
	ds_read_b128 v[198:201], v154 offset:4704
	ds_read_b128 v[206:209], v154 offset:9312
	ds_read_b128 v[214:217], v154 offset:13920
	s_waitcnt lgkmcnt(10)
	v_mfma_f32_32x32x16_bf16 v[80:95], v[194:197], v[148:151], v[80:95]
	v_mfma_f32_32x32x16_bf16 v[64:79], v[194:197], v[172:175], v[64:79]
	s_waitcnt lgkmcnt(9)
	v_mfma_f32_32x32x16_bf16 v[48:63], v[202:205], v[148:151], v[48:63]
	v_mfma_f32_32x32x16_bf16 v[32:47], v[202:205], v[172:175], v[32:47]
	s_waitcnt lgkmcnt(8)
	v_mfma_f32_32x32x16_bf16 v[16:31], v[210:213], v[148:151], v[16:31]
	v_mfma_f32_32x32x16_bf16 v[0:15], v[210:213], v[172:175], v[0:15]
	v_mfma_f32_32x32x16_bf16 v[112:127], v[186:189], v[148:151], v[112:127]
	v_mfma_f32_32x32x16_bf16 v[96:111], v[186:189], v[172:175], v[96:111]
	s_waitcnt vmcnt(3)
	ds_write_b128 v165, v[130:133]
	s_waitcnt vmcnt(2)
	ds_write_b128 v166, v[138:141]
	s_waitcnt lgkmcnt(4)
	v_mfma_f32_32x32x16_bf16 v[80:95], v[198:201], v[144:147], v[80:95]
	v_mfma_f32_32x32x16_bf16 v[64:79], v[198:201], v[182:185], v[64:79]
	s_waitcnt lgkmcnt(3)
	v_mfma_f32_32x32x16_bf16 v[48:63], v[206:209], v[144:147], v[48:63]
	v_mfma_f32_32x32x16_bf16 v[32:47], v[206:209], v[182:185], v[32:47]
	s_waitcnt lgkmcnt(2)
	v_mfma_f32_32x32x16_bf16 v[16:31], v[214:217], v[144:147], v[16:31]
	v_mfma_f32_32x32x16_bf16 v[0:15], v[214:217], v[182:185], v[0:15]
	v_mfma_f32_32x32x16_bf16 v[112:127], v[190:193], v[144:147], v[112:127]
	v_mfma_f32_32x32x16_bf16 v[96:111], v[190:193], v[182:185], v[96:111]
	s_waitcnt vmcnt(1)
	ds_write_b128 v167, v[158:161]
	s_waitcnt vmcnt(0)
	ds_write_b128 v168, v[134:137]
	s_waitcnt lgkmcnt(0)
	s_barrier
	ds_read_b128 v[130:133], v169
	ds_read_b128 v[134:137], v169 offset:32
	ds_read_b128 v[138:141], v169 offset:4608
	ds_read_b128 v[144:147], v169 offset:4640
	ds_read_b128 v[148:151], v155
	ds_read_b128 v[158:161], v155 offset:32
	ds_read_b128 v[172:175], v155 offset:4608
	ds_read_b128 v[182:185], v155 offset:4640
	ds_read_b128 v[186:189], v155 offset:9216
	ds_read_b128 v[190:193], v155 offset:9248
	ds_read_b128 v[194:197], v155 offset:13824
	ds_read_b128 v[198:201], v155 offset:13856
	s_waitcnt lgkmcnt(5)
	v_mfma_f32_32x32x16_bf16 v[80:95], v[172:175], v[130:133], v[80:95]
	v_mfma_f32_32x32x16_bf16 v[64:79], v[172:175], v[138:141], v[64:79]
	s_waitcnt lgkmcnt(3)
	v_mfma_f32_32x32x16_bf16 v[48:63], v[186:189], v[130:133], v[48:63]
	v_mfma_f32_32x32x16_bf16 v[32:47], v[186:189], v[138:141], v[32:47]
	s_waitcnt lgkmcnt(1)
	v_mfma_f32_32x32x16_bf16 v[16:31], v[194:197], v[130:133], v[16:31]
	v_mfma_f32_32x32x16_bf16 v[0:15], v[194:197], v[138:141], v[0:15]
	v_mfma_f32_32x32x16_bf16 v[112:127], v[148:151], v[130:133], v[112:127]
	v_mfma_f32_32x32x16_bf16 v[96:111], v[148:151], v[138:141], v[96:111]
	ds_read_b128 v[130:133], v169 offset:64
	ds_read_b128 v[138:141], v169 offset:4672
	ds_read_b128 v[148:151], v155 offset:64
	ds_read_b128 v[172:175], v155 offset:4672
	ds_read_b128 v[186:189], v155 offset:9280
	ds_read_b128 v[194:197], v155 offset:13888
	v_mfma_f32_32x32x16_bf16 v[80:95], v[182:185], v[134:137], v[80:95]
	v_mfma_f32_32x32x16_bf16 v[64:79], v[182:185], v[144:147], v[64:79]
	v_mfma_f32_32x32x16_bf16 v[48:63], v[190:193], v[134:137], v[48:63]
	v_mfma_f32_32x32x16_bf16 v[32:47], v[190:193], v[144:147], v[32:47]
	s_waitcnt lgkmcnt(6)
	v_mfma_f32_32x32x16_bf16 v[16:31], v[198:201], v[134:137], v[16:31]
	v_mfma_f32_32x32x16_bf16 v[0:15], v[198:201], v[144:147], v[0:15]
	v_mfma_f32_32x32x16_bf16 v[112:127], v[158:161], v[134:137], v[112:127]
	v_mfma_f32_32x32x16_bf16 v[96:111], v[158:161], v[144:147], v[96:111]
	ds_read_b128 v[134:137], v169 offset:96
	ds_read_b128 v[144:147], v169 offset:4704
	ds_read_b128 v[158:161], v155 offset:96
	ds_read_b128 v[182:185], v155 offset:4704
	ds_read_b128 v[190:193], v155 offset:9312
	ds_read_b128 v[198:201], v155 offset:13920
	s_waitcnt lgkmcnt(8)
	v_mfma_f32_32x32x16_bf16 v[80:95], v[172:175], v[130:133], v[80:95]
	v_mfma_f32_32x32x16_bf16 v[64:79], v[172:175], v[138:141], v[64:79]
	s_waitcnt lgkmcnt(7)
	v_mfma_f32_32x32x16_bf16 v[48:63], v[186:189], v[130:133], v[48:63]
	v_mfma_f32_32x32x16_bf16 v[32:47], v[186:189], v[138:141], v[32:47]
	s_waitcnt lgkmcnt(6)
	v_mfma_f32_32x32x16_bf16 v[16:31], v[194:197], v[130:133], v[16:31]
	v_mfma_f32_32x32x16_bf16 v[0:15], v[194:197], v[138:141], v[0:15]
	v_mfma_f32_32x32x16_bf16 v[112:127], v[148:151], v[130:133], v[112:127]
	v_mfma_f32_32x32x16_bf16 v[96:111], v[148:151], v[138:141], v[96:111]
	s_waitcnt lgkmcnt(2)
	v_mfma_f32_32x32x16_bf16 v[80:95], v[182:185], v[134:137], v[80:95]
	v_mfma_f32_32x32x16_bf16 v[64:79], v[182:185], v[144:147], v[64:79]
	s_waitcnt lgkmcnt(1)
	v_mfma_f32_32x32x16_bf16 v[48:63], v[190:193], v[134:137], v[48:63]
	v_mfma_f32_32x32x16_bf16 v[32:47], v[190:193], v[144:147], v[32:47]
	s_waitcnt lgkmcnt(0)
	v_mfma_f32_32x32x16_bf16 v[16:31], v[198:201], v[134:137], v[16:31]
	v_mfma_f32_32x32x16_bf16 v[0:15], v[198:201], v[144:147], v[0:15]
	v_mfma_f32_32x32x16_bf16 v[112:127], v[158:161], v[134:137], v[112:127]
	v_mfma_f32_32x32x16_bf16 v[96:111], v[158:161], v[144:147], v[96:111]
	v_add_u32_e32 v130, s1, v179
	s_movk_i32 s1, 0x7fff
	v_ashrrev_i32_e32 v131, 31, v130
	v_cmp_gt_i32_e32 vcc, s1, v130
	v_lshl_add_u64 v[134:135], v[130:131], 1, s[86:87]
	s_nop 5
	v_bfe_u32 v130, v112, 16, 1
	v_add3_u32 v112, v112, v130, s24
	s_barrier
	ds_write_b16_d16_hi v156, v112
	v_bfe_u32 v112, v113, 16, 1
	v_add3_u32 v112, v113, v112, s24
	ds_write_b16_d16_hi v156, v112 offset:144
	v_bfe_u32 v112, v114, 16, 1
	v_add3_u32 v112, v114, v112, s24
	ds_write_b16_d16_hi v156, v112 offset:288
	v_bfe_u32 v112, v115, 16, 1
	v_add3_u32 v112, v115, v112, s24
	ds_write_b16_d16_hi v156, v112 offset:432
	v_bfe_u32 v112, v116, 16, 1
	v_add3_u32 v112, v116, v112, s24
	ds_write_b16_d16_hi v156, v112 offset:1152
	v_bfe_u32 v112, v117, 16, 1
	v_add3_u32 v112, v117, v112, s24
	ds_write_b16_d16_hi v156, v112 offset:1296
	v_bfe_u32 v112, v118, 16, 1
	v_add3_u32 v112, v118, v112, s24
	ds_write_b16_d16_hi v156, v112 offset:1440
	v_bfe_u32 v112, v119, 16, 1
	v_add3_u32 v112, v119, v112, s24
	ds_write_b16_d16_hi v156, v112 offset:1584
	v_bfe_u32 v112, v120, 16, 1
	v_add3_u32 v112, v120, v112, s24
	ds_write_b16_d16_hi v156, v112 offset:2304
	v_bfe_u32 v112, v121, 16, 1
	v_add3_u32 v112, v121, v112, s24
	ds_write_b16_d16_hi v156, v112 offset:2448
	v_bfe_u32 v112, v122, 16, 1
	v_add3_u32 v112, v122, v112, s24
	ds_write_b16_d16_hi v156, v112 offset:2592
	v_bfe_u32 v112, v123, 16, 1
	v_add3_u32 v112, v123, v112, s24
	ds_write_b16_d16_hi v156, v112 offset:2736
	v_bfe_u32 v112, v124, 16, 1
	v_add3_u32 v112, v124, v112, s24
	ds_write_b16_d16_hi v156, v112 offset:3456
	v_bfe_u32 v112, v125, 16, 1
	v_add3_u32 v112, v125, v112, s24
	ds_write_b16_d16_hi v156, v112 offset:3600
	v_bfe_u32 v112, v126, 16, 1
	v_add3_u32 v112, v126, v112, s24
	ds_write_b16_d16_hi v156, v112 offset:3744
	v_bfe_u32 v112, v127, 16, 1
	v_add3_u32 v112, v127, v112, s24
	ds_write_b16_d16_hi v156, v112 offset:3888
	v_bfe_u32 v112, v96, 16, 1
	v_add3_u32 v96, v96, v112, s24
	ds_write_b16_d16_hi v156, v96 offset:64
	v_bfe_u32 v96, v97, 16, 1
	v_add3_u32 v96, v97, v96, s24
	ds_write_b16_d16_hi v156, v96 offset:208
	v_bfe_u32 v96, v98, 16, 1
	v_add3_u32 v96, v98, v96, s24
	ds_write_b16_d16_hi v156, v96 offset:352
	v_bfe_u32 v96, v99, 16, 1
	v_add3_u32 v96, v99, v96, s24
	ds_write_b16_d16_hi v156, v96 offset:496
	v_bfe_u32 v96, v100, 16, 1
	v_add3_u32 v96, v100, v96, s24
	ds_write_b16_d16_hi v156, v96 offset:1216
	v_bfe_u32 v96, v101, 16, 1
	v_add3_u32 v96, v101, v96, s24
	ds_write_b16_d16_hi v156, v96 offset:1360
	v_bfe_u32 v96, v102, 16, 1
	v_add3_u32 v96, v102, v96, s24
	ds_write_b16_d16_hi v156, v96 offset:1504
	v_bfe_u32 v96, v103, 16, 1
	v_add3_u32 v96, v103, v96, s24
	ds_write_b16_d16_hi v156, v96 offset:1648
	v_bfe_u32 v96, v104, 16, 1
	v_add3_u32 v96, v104, v96, s24
	ds_write_b16_d16_hi v156, v96 offset:2368
	v_bfe_u32 v96, v105, 16, 1
	v_add3_u32 v96, v105, v96, s24
	ds_write_b16_d16_hi v156, v96 offset:2512
	v_bfe_u32 v96, v106, 16, 1
	v_add3_u32 v96, v106, v96, s24
	ds_write_b16_d16_hi v156, v96 offset:2656
	v_bfe_u32 v96, v107, 16, 1
	v_add3_u32 v96, v107, v96, s24
	ds_write_b16_d16_hi v156, v96 offset:2800
	v_bfe_u32 v96, v108, 16, 1
	v_add3_u32 v96, v108, v96, s24
	ds_write_b16_d16_hi v156, v96 offset:3520
	v_bfe_u32 v96, v109, 16, 1
	v_add3_u32 v96, v109, v96, s24
	ds_write_b16_d16_hi v156, v96 offset:3664
	v_bfe_u32 v96, v110, 16, 1
	v_add3_u32 v96, v110, v96, s24
	ds_write_b16_d16_hi v156, v96 offset:3808
	v_bfe_u32 v96, v111, 16, 1
	v_add_u32_e32 v136, s0, v153
	v_add3_u32 v96, v111, v96, s24
	ds_write_b16_d16_hi v156, v96 offset:3952
	s_and_saveexec_b64 s[0:1], vcc
	s_cbranch_execz .Lgo_242
	ds_read_b128 v[96:99], v170
	v_or_b32_e32 v100, v136, v157
	v_mad_i64_i32 v[100:101], s[10:11], v100, s88, v[134:135]
	s_waitcnt lgkmcnt(0)
	global_store_dwordx4 v[100:101], v[96:99], off
	ds_read_b128 v[96:99], v170 offset:1152
	v_or_b32_e32 v100, v136, v171
	v_mad_i64_i32 v[100:101], s[10:11], v100, s88, v[134:135]
	s_waitcnt lgkmcnt(0)
	global_store_dwordx4 v[100:101], v[96:99], off
	ds_read_b128 v[96:99], v170 offset:2304
	v_or_b32_e32 v100, v136, v252
	v_mad_i64_i32 v[100:101], s[10:11], v100, s88, v[134:135]
	s_waitcnt lgkmcnt(0)
	global_store_dwordx4 v[100:101], v[96:99], off
	ds_read_b128 v[96:99], v170 offset:3456
	v_or_b32_e32 v100, v136, v181
	v_mad_i64_i32 v[100:101], s[10:11], v100, s88, v[134:135]
	s_waitcnt lgkmcnt(0)
	global_store_dwordx4 v[100:101], v[96:99], off
.Lgo_242:
	s_or_b64 exec, exec, s[0:1]
	s_nop 0
	v_bfe_u32 v96, v80, 16, 1
	v_add3_u32 v80, v80, v96, s24
	ds_write_b16_d16_hi v156, v80
	v_bfe_u32 v80, v81, 16, 1
	v_add3_u32 v80, v81, v80, s24
	ds_write_b16_d16_hi v156, v80 offset:144
	v_bfe_u32 v80, v82, 16, 1
	v_add3_u32 v80, v82, v80, s24
	ds_write_b16_d16_hi v156, v80 offset:288
	v_bfe_u32 v80, v83, 16, 1
	v_add3_u32 v80, v83, v80, s24
	ds_write_b16_d16_hi v156, v80 offset:432
	v_bfe_u32 v80, v84, 16, 1
	v_add3_u32 v80, v84, v80, s24
	ds_write_b16_d16_hi v156, v80 offset:1152
	v_bfe_u32 v80, v85, 16, 1
	v_add3_u32 v80, v85, v80, s24
	ds_write_b16_d16_hi v156, v80 offset:1296
	v_bfe_u32 v80, v86, 16, 1
	v_add3_u32 v80, v86, v80, s24
	ds_write_b16_d16_hi v156, v80 offset:1440
	v_bfe_u32 v80, v87, 16, 1
	v_add3_u32 v80, v87, v80, s24
	ds_write_b16_d16_hi v156, v80 offset:1584
	v_bfe_u32 v80, v88, 16, 1
	v_add3_u32 v80, v88, v80, s24
	ds_write_b16_d16_hi v156, v80 offset:2304
	v_bfe_u32 v80, v89, 16, 1
	v_add3_u32 v80, v89, v80, s24
	ds_write_b16_d16_hi v156, v80 offset:2448
	v_bfe_u32 v80, v90, 16, 1
	v_add3_u32 v80, v90, v80, s24
	ds_write_b16_d16_hi v156, v80 offset:2592
	v_bfe_u32 v80, v91, 16, 1
	v_add3_u32 v80, v91, v80, s24
	ds_write_b16_d16_hi v156, v80 offset:2736
	v_bfe_u32 v80, v92, 16, 1
	v_add3_u32 v80, v92, v80, s24
	ds_write_b16_d16_hi v156, v80 offset:3456
	v_bfe_u32 v80, v93, 16, 1
	v_add3_u32 v80, v93, v80, s24
	ds_write_b16_d16_hi v156, v80 offset:3600
	v_bfe_u32 v80, v94, 16, 1
	v_add3_u32 v80, v94, v80, s24
	ds_write_b16_d16_hi v156, v80 offset:3744
	v_bfe_u32 v80, v95, 16, 1
	v_add3_u32 v80, v95, v80, s24
	ds_write_b16_d16_hi v156, v80 offset:3888
	v_bfe_u32 v80, v64, 16, 1
	v_add3_u32 v64, v64, v80, s24
	ds_write_b16_d16_hi v156, v64 offset:64
	v_bfe_u32 v64, v65, 16, 1
	v_add3_u32 v64, v65, v64, s24
	ds_write_b16_d16_hi v156, v64 offset:208
	v_bfe_u32 v64, v66, 16, 1
	v_add3_u32 v64, v66, v64, s24
	ds_write_b16_d16_hi v156, v64 offset:352
	v_bfe_u32 v64, v67, 16, 1
	v_add3_u32 v64, v67, v64, s24
	ds_write_b16_d16_hi v156, v64 offset:496
	v_bfe_u32 v64, v68, 16, 1
	v_add3_u32 v64, v68, v64, s24
	ds_write_b16_d16_hi v156, v64 offset:1216
	v_bfe_u32 v64, v69, 16, 1
	v_add3_u32 v64, v69, v64, s24
	ds_write_b16_d16_hi v156, v64 offset:1360
	v_bfe_u32 v64, v70, 16, 1
	v_add3_u32 v64, v70, v64, s24
	ds_write_b16_d16_hi v156, v64 offset:1504
	v_bfe_u32 v64, v71, 16, 1
	v_add3_u32 v64, v71, v64, s24
	ds_write_b16_d16_hi v156, v64 offset:1648
	v_bfe_u32 v64, v72, 16, 1
	v_add3_u32 v64, v72, v64, s24
	ds_write_b16_d16_hi v156, v64 offset:2368
	v_bfe_u32 v64, v73, 16, 1
	v_add3_u32 v64, v73, v64, s24
	ds_write_b16_d16_hi v156, v64 offset:2512
	v_bfe_u32 v64, v74, 16, 1
	v_add3_u32 v64, v74, v64, s24
	ds_write_b16_d16_hi v156, v64 offset:2656
	v_bfe_u32 v64, v75, 16, 1
	v_add3_u32 v64, v75, v64, s24
	ds_write_b16_d16_hi v156, v64 offset:2800
	v_bfe_u32 v64, v76, 16, 1
	v_add3_u32 v64, v76, v64, s24
	ds_write_b16_d16_hi v156, v64 offset:3520
	v_bfe_u32 v64, v77, 16, 1
	v_add3_u32 v64, v77, v64, s24
	ds_write_b16_d16_hi v156, v64 offset:3664
	v_bfe_u32 v64, v78, 16, 1
	v_add3_u32 v64, v78, v64, s24
	ds_write_b16_d16_hi v156, v64 offset:3808
	v_bfe_u32 v64, v79, 16, 1
	v_add3_u32 v64, v79, v64, s24
	ds_write_b16_d16_hi v156, v64 offset:3952
	s_and_saveexec_b64 s[0:1], vcc
	s_cbranch_execz .Lgo_244
	ds_read_b128 v[64:67], v170
	v_or_b32_e32 v70, 32, v136
	v_or_b32_e32 v68, v70, v157
	v_mad_i64_i32 v[68:69], s[10:11], v68, s88, v[134:135]
	s_waitcnt lgkmcnt(0)
	global_store_dwordx4 v[68:69], v[64:67], off
	ds_read_b128 v[64:67], v170 offset:1152
	v_or_b32_e32 v68, v70, v171
	v_mad_i64_i32 v[68:69], s[10:11], v68, s88, v[134:135]
	s_waitcnt lgkmcnt(0)
	global_store_dwordx4 v[68:69], v[64:67], off
	ds_read_b128 v[64:67], v170 offset:2304
	v_or_b32_e32 v68, v70, v252
	v_mad_i64_i32 v[68:69], s[10:11], v68, s88, v[134:135]
	s_waitcnt lgkmcnt(0)
	global_store_dwordx4 v[68:69], v[64:67], off
	ds_read_b128 v[64:67], v170 offset:3456
	v_or_b32_e32 v68, v70, v181
	v_mad_i64_i32 v[68:69], s[10:11], v68, s88, v[134:135]
	s_waitcnt lgkmcnt(0)
	global_store_dwordx4 v[68:69], v[64:67], off
.Lgo_244:
	s_or_b64 exec, exec, s[0:1]
	s_nop 0
	v_bfe_u32 v64, v48, 16, 1
	v_add3_u32 v48, v48, v64, s24
	ds_write_b16_d16_hi v156, v48
	v_bfe_u32 v48, v49, 16, 1
	v_add3_u32 v48, v49, v48, s24
	ds_write_b16_d16_hi v156, v48 offset:144
	v_bfe_u32 v48, v50, 16, 1
	v_add3_u32 v48, v50, v48, s24
	ds_write_b16_d16_hi v156, v48 offset:288
	v_bfe_u32 v48, v51, 16, 1
	v_add3_u32 v48, v51, v48, s24
	ds_write_b16_d16_hi v156, v48 offset:432
	v_bfe_u32 v48, v52, 16, 1
	v_add3_u32 v48, v52, v48, s24
	ds_write_b16_d16_hi v156, v48 offset:1152
	v_bfe_u32 v48, v53, 16, 1
	v_add3_u32 v48, v53, v48, s24
	ds_write_b16_d16_hi v156, v48 offset:1296
	v_bfe_u32 v48, v54, 16, 1
	v_add3_u32 v48, v54, v48, s24
	ds_write_b16_d16_hi v156, v48 offset:1440
	v_bfe_u32 v48, v55, 16, 1
	v_add3_u32 v48, v55, v48, s24
	ds_write_b16_d16_hi v156, v48 offset:1584
	v_bfe_u32 v48, v56, 16, 1
	v_add3_u32 v48, v56, v48, s24
	ds_write_b16_d16_hi v156, v48 offset:2304
	v_bfe_u32 v48, v57, 16, 1
	v_add3_u32 v48, v57, v48, s24
	ds_write_b16_d16_hi v156, v48 offset:2448
	v_bfe_u32 v48, v58, 16, 1
	v_add3_u32 v48, v58, v48, s24
	ds_write_b16_d16_hi v156, v48 offset:2592
	v_bfe_u32 v48, v59, 16, 1
	v_add3_u32 v48, v59, v48, s24
	ds_write_b16_d16_hi v156, v48 offset:2736
	v_bfe_u32 v48, v60, 16, 1
	v_add3_u32 v48, v60, v48, s24
	ds_write_b16_d16_hi v156, v48 offset:3456
	v_bfe_u32 v48, v61, 16, 1
	v_add3_u32 v48, v61, v48, s24
	ds_write_b16_d16_hi v156, v48 offset:3600
	v_bfe_u32 v48, v62, 16, 1
	v_add3_u32 v48, v62, v48, s24
	ds_write_b16_d16_hi v156, v48 offset:3744
	v_bfe_u32 v48, v63, 16, 1
	v_add3_u32 v48, v63, v48, s24
	ds_write_b16_d16_hi v156, v48 offset:3888
	v_bfe_u32 v48, v32, 16, 1
	v_add3_u32 v32, v32, v48, s24
	ds_write_b16_d16_hi v156, v32 offset:64
	v_bfe_u32 v32, v33, 16, 1
	v_add3_u32 v32, v33, v32, s24
	ds_write_b16_d16_hi v156, v32 offset:208
	v_bfe_u32 v32, v34, 16, 1
	v_add3_u32 v32, v34, v32, s24
	ds_write_b16_d16_hi v156, v32 offset:352
	v_bfe_u32 v32, v35, 16, 1
	v_add3_u32 v32, v35, v32, s24
	ds_write_b16_d16_hi v156, v32 offset:496
	v_bfe_u32 v32, v36, 16, 1
	v_add3_u32 v32, v36, v32, s24
	ds_write_b16_d16_hi v156, v32 offset:1216
	v_bfe_u32 v32, v37, 16, 1
	v_add3_u32 v32, v37, v32, s24
	ds_write_b16_d16_hi v156, v32 offset:1360
	v_bfe_u32 v32, v38, 16, 1
	v_add3_u32 v32, v38, v32, s24
	ds_write_b16_d16_hi v156, v32 offset:1504
	v_bfe_u32 v32, v39, 16, 1
	v_add3_u32 v32, v39, v32, s24
	ds_write_b16_d16_hi v156, v32 offset:1648
	v_bfe_u32 v32, v40, 16, 1
	v_add3_u32 v32, v40, v32, s24
	ds_write_b16_d16_hi v156, v32 offset:2368
	v_bfe_u32 v32, v41, 16, 1
	v_add3_u32 v32, v41, v32, s24
	ds_write_b16_d16_hi v156, v32 offset:2512
	v_bfe_u32 v32, v42, 16, 1
	v_add3_u32 v32, v42, v32, s24
	ds_write_b16_d16_hi v156, v32 offset:2656
	v_bfe_u32 v32, v43, 16, 1
	v_add3_u32 v32, v43, v32, s24
	ds_write_b16_d16_hi v156, v32 offset:2800
	v_bfe_u32 v32, v44, 16, 1
	v_add3_u32 v32, v44, v32, s24
	ds_write_b16_d16_hi v156, v32 offset:3520
	v_bfe_u32 v32, v45, 16, 1
	v_add3_u32 v32, v45, v32, s24
	ds_write_b16_d16_hi v156, v32 offset:3664
	v_bfe_u32 v32, v46, 16, 1
	v_add3_u32 v32, v46, v32, s24
	ds_write_b16_d16_hi v156, v32 offset:3808
	v_bfe_u32 v32, v47, 16, 1
	v_add3_u32 v32, v47, v32, s24
	ds_write_b16_d16_hi v156, v32 offset:3952
	s_and_saveexec_b64 s[0:1], vcc
	s_cbranch_execz .Lgo_246
	ds_read_b128 v[32:35], v170
	v_or_b32_e32 v38, 64, v136
	v_or_b32_e32 v36, v38, v157
	v_mad_i64_i32 v[36:37], s[10:11], v36, s88, v[134:135]
	s_waitcnt lgkmcnt(0)
	global_store_dwordx4 v[36:37], v[32:35], off
	ds_read_b128 v[32:35], v170 offset:1152
	v_or_b32_e32 v36, v38, v171
	v_mad_i64_i32 v[36:37], s[10:11], v36, s88, v[134:135]
	s_waitcnt lgkmcnt(0)
	global_store_dwordx4 v[36:37], v[32:35], off
	ds_read_b128 v[32:35], v170 offset:2304
	v_or_b32_e32 v36, v38, v252
	v_mad_i64_i32 v[36:37], s[10:11], v36, s88, v[134:135]
	s_waitcnt lgkmcnt(0)
	global_store_dwordx4 v[36:37], v[32:35], off
	ds_read_b128 v[32:35], v170 offset:3456
	v_or_b32_e32 v36, v38, v181
	v_mad_i64_i32 v[36:37], s[10:11], v36, s88, v[134:135]
	s_waitcnt lgkmcnt(0)
	global_store_dwordx4 v[36:37], v[32:35], off
.Lgo_246:
	s_or_b64 exec, exec, s[0:1]
	s_nop 0
	v_bfe_u32 v32, v16, 16, 1
	v_add3_u32 v16, v16, v32, s24
	ds_write_b16_d16_hi v156, v16
	v_bfe_u32 v16, v17, 16, 1
	v_add3_u32 v16, v17, v16, s24
	ds_write_b16_d16_hi v156, v16 offset:144
	v_bfe_u32 v16, v18, 16, 1
	v_add3_u32 v16, v18, v16, s24
	ds_write_b16_d16_hi v156, v16 offset:288
	v_bfe_u32 v16, v19, 16, 1
	v_add3_u32 v16, v19, v16, s24
	ds_write_b16_d16_hi v156, v16 offset:432
	v_bfe_u32 v16, v20, 16, 1
	v_add3_u32 v16, v20, v16, s24
	ds_write_b16_d16_hi v156, v16 offset:1152
	v_bfe_u32 v16, v21, 16, 1
	v_add3_u32 v16, v21, v16, s24
	ds_write_b16_d16_hi v156, v16 offset:1296
	v_bfe_u32 v16, v22, 16, 1
	v_add3_u32 v16, v22, v16, s24
	ds_write_b16_d16_hi v156, v16 offset:1440
	v_bfe_u32 v16, v23, 16, 1
	v_add3_u32 v16, v23, v16, s24
	ds_write_b16_d16_hi v156, v16 offset:1584
	v_bfe_u32 v16, v24, 16, 1
	v_add3_u32 v16, v24, v16, s24
	ds_write_b16_d16_hi v156, v16 offset:2304
	v_bfe_u32 v16, v25, 16, 1
	v_add3_u32 v16, v25, v16, s24
	ds_write_b16_d16_hi v156, v16 offset:2448
	v_bfe_u32 v16, v26, 16, 1
	v_add3_u32 v16, v26, v16, s24
	ds_write_b16_d16_hi v156, v16 offset:2592
	v_bfe_u32 v16, v27, 16, 1
	v_add3_u32 v16, v27, v16, s24
	ds_write_b16_d16_hi v156, v16 offset:2736
	v_bfe_u32 v16, v28, 16, 1
	v_add3_u32 v16, v28, v16, s24
	ds_write_b16_d16_hi v156, v16 offset:3456
	v_bfe_u32 v16, v29, 16, 1
	v_add3_u32 v16, v29, v16, s24
	ds_write_b16_d16_hi v156, v16 offset:3600
	v_bfe_u32 v16, v30, 16, 1
	v_add3_u32 v16, v30, v16, s24
	ds_write_b16_d16_hi v156, v16 offset:3744
	v_bfe_u32 v16, v31, 16, 1
	v_add3_u32 v16, v31, v16, s24
	ds_write_b16_d16_hi v156, v16 offset:3888
	v_bfe_u32 v16, v0, 16, 1
	v_add3_u32 v0, v0, v16, s24
	ds_write_b16_d16_hi v156, v0 offset:64
	v_bfe_u32 v0, v1, 16, 1
	v_add3_u32 v0, v1, v0, s24
	ds_write_b16_d16_hi v156, v0 offset:208
	v_bfe_u32 v0, v2, 16, 1
	v_add3_u32 v0, v2, v0, s24
	ds_write_b16_d16_hi v156, v0 offset:352
	v_bfe_u32 v0, v3, 16, 1
	v_add3_u32 v0, v3, v0, s24
	ds_write_b16_d16_hi v156, v0 offset:496
	v_bfe_u32 v0, v4, 16, 1
	v_add3_u32 v0, v4, v0, s24
	ds_write_b16_d16_hi v156, v0 offset:1216
	v_bfe_u32 v0, v5, 16, 1
	v_add3_u32 v0, v5, v0, s24
	ds_write_b16_d16_hi v156, v0 offset:1360
	v_bfe_u32 v0, v6, 16, 1
	v_add3_u32 v0, v6, v0, s24
	ds_write_b16_d16_hi v156, v0 offset:1504
	v_bfe_u32 v0, v7, 16, 1
	v_add3_u32 v0, v7, v0, s24
	ds_write_b16_d16_hi v156, v0 offset:1648
	v_bfe_u32 v0, v8, 16, 1
	v_add3_u32 v0, v8, v0, s24
	ds_write_b16_d16_hi v156, v0 offset:2368
	v_bfe_u32 v0, v9, 16, 1
	v_add3_u32 v0, v9, v0, s24
	ds_write_b16_d16_hi v156, v0 offset:2512
	v_bfe_u32 v0, v10, 16, 1
	v_add3_u32 v0, v10, v0, s24
	ds_write_b16_d16_hi v156, v0 offset:2656
	v_bfe_u32 v0, v11, 16, 1
	v_add3_u32 v0, v11, v0, s24
	ds_write_b16_d16_hi v156, v0 offset:2800
	v_bfe_u32 v0, v12, 16, 1
	v_add3_u32 v0, v12, v0, s24
	ds_write_b16_d16_hi v156, v0 offset:3520
	v_bfe_u32 v0, v13, 16, 1
	v_add3_u32 v0, v13, v0, s24
	ds_write_b16_d16_hi v156, v0 offset:3664
	v_bfe_u32 v0, v14, 16, 1
	v_add3_u32 v0, v14, v0, s24
	ds_write_b16_d16_hi v156, v0 offset:3808
	v_bfe_u32 v0, v15, 16, 1
	v_add3_u32 v0, v15, v0, s24
	ds_write_b16_d16_hi v156, v0 offset:3952
	s_and_saveexec_b64 s[0:1], vcc
	s_cbranch_execz .Lgo_237
	ds_read_b128 v[0:3], v170
	v_or_b32_e32 v6, 0x60, v136
	v_or_b32_e32 v4, v6, v157
	v_mad_i64_i32 v[4:5], s[10:11], v4, s88, v[134:135]
	s_waitcnt lgkmcnt(0)
	global_store_dwordx4 v[4:5], v[0:3], off
	ds_read_b128 v[0:3], v170 offset:1152
	v_or_b32_e32 v4, v6, v171
	v_mad_i64_i32 v[4:5], s[10:11], v4, s88, v[134:135]
	s_waitcnt lgkmcnt(0)
	global_store_dwordx4 v[4:5], v[0:3], off
	ds_read_b128 v[0:3], v170 offset:2304
	v_or_b32_e32 v4, v6, v252
	v_mad_i64_i32 v[4:5], s[10:11], v4, s88, v[134:135]
	s_waitcnt lgkmcnt(0)
	global_store_dwordx4 v[4:5], v[0:3], off
	ds_read_b128 v[0:3], v170 offset:3456
	v_or_b32_e32 v4, v6, v181
	v_mad_i64_i32 v[4:5], s[10:11], v4, s88, v[134:135]
	s_waitcnt lgkmcnt(0)
	global_store_dwordx4 v[4:5], v[0:3], off
	s_branch .Lgo_237

.Lgo_end:
	s_branch .LBB0_1191
	s_cbranch_vccz .LBB0_1183
	v_readlane_b32 s6, v255, 23
	s_mov_b32 s1, 0
	s_mov_b32 s0, 0
	v_readlane_b32 s4, v253, 0
	v_readlane_b32 s7, v255, 24
	s_mov_b32 s5, s6
	s_branch .LBB0_1184
